# conversion output stores write-through (sc1) so slot conversion leaves no dirty L2 lines at the barrier
# speedup vs baseline: 1.0022x; 1.0022x over previous
.LBB0_20:
	v_lshl_add_u64 v[36:37], v[20:21], 0, s[20:21]
	v_lshl_add_u64 v[38:39], v[18:19], 0, s[20:21]
	v_lshl_add_u64 v[40:41], v[16:17], 0, s[20:21]
	v_lshl_add_u64 v[42:43], v[14:15], 0, s[20:21]
	v_lshl_add_u64 v[44:45], v[12:13], 0, s[20:21]
	v_lshl_add_u64 v[46:47], v[10:11], 0, s[20:21]
	v_lshl_add_u64 v[48:49], v[8:9], 0, s[20:21]
	v_lshl_add_u64 v[50:51], v[6:7], 0, s[20:21]
	global_load_dword v52, v[36:37], off nt
	global_load_dword v53, v[38:39], off nt
	global_load_dword v54, v[40:41], off nt
	global_load_dword v55, v[42:43], off nt
	global_load_dword v56, v[44:45], off nt
	global_load_dword v57, v[46:47], off nt
	global_load_dword v58, v[48:49], off nt
	global_load_dword v59, v[50:51], off nt
	s_add_u32 s20, s20, 0x20000
	s_addc_u32 s21, s21, 0
	v_lshl_add_u64 v[36:37], v[20:21], 0, s[20:21]
	v_lshl_add_u64 v[38:39], v[18:19], 0, s[20:21]
	v_lshl_add_u64 v[40:41], v[16:17], 0, s[20:21]
	v_lshl_add_u64 v[42:43], v[14:15], 0, s[20:21]
	v_lshl_add_u64 v[44:45], v[12:13], 0, s[20:21]
	v_lshl_add_u64 v[46:47], v[10:11], 0, s[20:21]
	v_lshl_add_u64 v[48:49], v[8:9], 0, s[20:21]
	v_lshl_add_u64 v[50:51], v[6:7], 0, s[20:21]
	global_load_dword v60, v[36:37], off nt
	global_load_dword v61, v[38:39], off nt
	global_load_dword v62, v[40:41], off nt
	global_load_dword v63, v[42:43], off nt
	global_load_dword v64, v[44:45], off nt
	global_load_dword v65, v[46:47], off nt
	global_load_dword v66, v[48:49], off nt
	global_load_dword v67, v[50:51], off nt
	s_add_u32 s20, s20, 0x20000
	s_addc_u32 s21, s21, 0
	v_lshl_add_u64 v[36:37], v[20:21], 0, s[20:21]
	v_lshl_add_u64 v[38:39], v[18:19], 0, s[20:21]
	v_lshl_add_u64 v[40:41], v[16:17], 0, s[20:21]
	v_lshl_add_u64 v[42:43], v[14:15], 0, s[20:21]
	v_lshl_add_u64 v[44:45], v[12:13], 0, s[20:21]
	v_lshl_add_u64 v[46:47], v[10:11], 0, s[20:21]
	v_lshl_add_u64 v[48:49], v[8:9], 0, s[20:21]
	v_lshl_add_u64 v[50:51], v[6:7], 0, s[20:21]
	global_load_dword v68, v[36:37], off nt
	global_load_dword v69, v[38:39], off nt
	global_load_dword v70, v[40:41], off nt
	global_load_dword v71, v[42:43], off nt
	global_load_dword v72, v[44:45], off nt
	global_load_dword v73, v[46:47], off nt
	global_load_dword v74, v[48:49], off nt
	global_load_dword v75, v[50:51], off nt
	s_add_u32 s20, s20, 0x20000
	s_addc_u32 s21, s21, 0
	v_lshl_add_u64 v[36:37], v[20:21], 0, s[20:21]
	v_lshl_add_u64 v[38:39], v[18:19], 0, s[20:21]
	v_lshl_add_u64 v[40:41], v[16:17], 0, s[20:21]
	v_lshl_add_u64 v[42:43], v[14:15], 0, s[20:21]
	v_lshl_add_u64 v[44:45], v[12:13], 0, s[20:21]
	v_lshl_add_u64 v[46:47], v[10:11], 0, s[20:21]
	v_lshl_add_u64 v[48:49], v[8:9], 0, s[20:21]
	v_lshl_add_u64 v[50:51], v[6:7], 0, s[20:21]
	global_load_dword v76, v[36:37], off nt
	global_load_dword v77, v[38:39], off nt
	global_load_dword v78, v[40:41], off nt
	global_load_dword v79, v[42:43], off nt
	global_load_dword v80, v[44:45], off nt
	global_load_dword v81, v[46:47], off nt
	global_load_dword v82, v[48:49], off nt
	global_load_dword v83, v[50:51], off nt
	s_add_u32 s20, s20, 0x20000
	s_addc_u32 s21, s21, 0
	v_add_u32_e32 v36, 0x400, v35
	s_waitcnt vmcnt(30)
	ds_write2_b32 v35, v52, v53 offset1:66
	s_waitcnt vmcnt(28)
	ds_write2_b32 v35, v54, v55 offset0:132 offset1:198
	s_waitcnt vmcnt(26)
	ds_write2_b32 v36, v56, v57 offset0:8 offset1:74
	s_waitcnt vmcnt(24)
	ds_write2_b32 v36, v58, v59 offset0:140 offset1:206
	v_add_u32_e32 v35, 0x840, v35
	v_add_u32_e32 v36, 0x400, v35
	s_waitcnt vmcnt(22)
	ds_write2_b32 v35, v60, v61 offset1:66
	s_waitcnt vmcnt(20)
	ds_write2_b32 v35, v62, v63 offset0:132 offset1:198
	s_waitcnt vmcnt(18)
	ds_write2_b32 v36, v64, v65 offset0:8 offset1:74
	s_waitcnt vmcnt(16)
	ds_write2_b32 v36, v66, v67 offset0:140 offset1:206
	v_add_u32_e32 v35, 0x840, v35
	v_add_u32_e32 v36, 0x400, v35
	s_waitcnt vmcnt(14)
	ds_write2_b32 v35, v68, v69 offset1:66
	s_waitcnt vmcnt(12)
	ds_write2_b32 v35, v70, v71 offset0:132 offset1:198
	s_waitcnt vmcnt(10)
	ds_write2_b32 v36, v72, v73 offset0:8 offset1:74
	s_waitcnt vmcnt(8)
	ds_write2_b32 v36, v74, v75 offset0:140 offset1:206
	v_add_u32_e32 v35, 0x840, v35
	v_add_u32_e32 v36, 0x400, v35
	s_waitcnt vmcnt(6)
	ds_write2_b32 v35, v76, v77 offset1:66
	s_waitcnt vmcnt(4)
	ds_write2_b32 v35, v78, v79 offset0:132 offset1:198
	s_waitcnt vmcnt(2)
	ds_write2_b32 v36, v80, v81 offset0:8 offset1:74
	s_waitcnt vmcnt(0)
	ds_write2_b32 v36, v82, v83 offset0:140 offset1:206
	v_add_u32_e32 v35, 0x840, v35
	s_waitcnt lgkmcnt(0)
	s_lshl_b32 s20, s22, 5
	ds_read2_b32 v[10:11], v23 offset1:8
	s_and_b32 s33, s20, 0x7e0
	s_lshl_b32 s20, s23, 1
	ds_read2_b32 v[14:15], v23 offset0:33 offset1:41
	s_add_u32 s20, s30, s20
	s_addc_u32 s21, s31, 0
	ds_read2_b32 v[16:17], v23 offset0:66 offset1:74
	v_lshl_add_u64 v[6:7], s[20:21], 0, v[2:3]
	ds_read2_b32 v[18:19], v23 offset0:99 offset1:107
	v_lshl_add_u64 v[12:13], v[6:7], 0, s[4:5]
	s_waitcnt lgkmcnt(3)
	v_bfe_u32 v6, v10, 16, 1
	v_add3_u32 v6, v10, v6, s26
	s_waitcnt lgkmcnt(2)
	v_bfe_u32 v7, v14, 16, 1
	ds_read2_b32 v[20:21], v23 offset0:132 offset1:140
	v_lshrrev_b32_e32 v6, 16, v6
	v_add3_u32 v7, v14, v7, s26
	ds_read2_b32 v[36:37], v23 offset0:165 offset1:173
	v_and_or_b32 v6, v7, s27, v6
	s_waitcnt lgkmcnt(3)
	v_bfe_u32 v7, v16, 16, 1
	v_add3_u32 v7, v16, v7, s26
	s_waitcnt lgkmcnt(2)
	v_bfe_u32 v8, v18, 16, 1
	ds_read2_b32 v[38:39], v23 offset0:198 offset1:206
	v_lshrrev_b32_e32 v7, 16, v7
	v_add3_u32 v8, v18, v8, s26
	ds_read2_b32 v[40:41], v23 offset0:231 offset1:239
	v_and_or_b32 v7, v8, s27, v7
	s_waitcnt lgkmcnt(3)
	v_bfe_u32 v8, v20, 16, 1
	v_add3_u32 v8, v20, v8, s26
	s_waitcnt lgkmcnt(2)
	v_bfe_u32 v9, v36, 16, 1
	v_lshrrev_b32_e32 v8, 16, v8
	v_add3_u32 v9, v36, v9, s26
	v_and_or_b32 v8, v9, s27, v8
	s_waitcnt lgkmcnt(1)
	v_bfe_u32 v9, v38, 16, 1
	v_add3_u32 v9, v38, v9, s26
	s_waitcnt lgkmcnt(0)
	v_bfe_u32 v10, v40, 16, 1
	v_lshrrev_b32_e32 v9, 16, v9
	v_add3_u32 v10, v40, v10, s26
	v_and_or_b32 v9, v10, s27, v9
	v_or_b32_e32 v10, s33, v22
	v_mul_u32_u24_e32 v10, 0x1600, v10
	v_lshlrev_b32_e32 v42, 1, v10
	v_mov_b32_e32 v43, v3
	v_lshl_add_u64 v[42:43], v[12:13], 0, v[42:43]
	global_store_dwordx4 v[42:43], v[6:9], off sc1
	v_bfe_u32 v10, v41, 16, 1
	v_add3_u32 v10, v41, v10, s26
	v_bfe_u32 v6, v11, 16, 1
	v_add3_u32 v6, v11, v6, s26
	v_bfe_u32 v7, v15, 16, 1
	v_lshrrev_b32_e32 v6, 16, v6
	v_add3_u32 v7, v15, v7, s26
	v_and_or_b32 v6, v7, s27, v6
	v_bfe_u32 v7, v17, 16, 1
	v_add3_u32 v7, v17, v7, s26
	v_bfe_u32 v8, v19, 16, 1
	v_lshrrev_b32_e32 v7, 16, v7
	v_add3_u32 v8, v19, v8, s26
	v_and_or_b32 v7, v8, s27, v7
	v_bfe_u32 v8, v21, 16, 1
	v_add3_u32 v8, v21, v8, s26
	v_bfe_u32 v9, v37, 16, 1
	v_lshrrev_b32_e32 v8, 16, v8
	v_add3_u32 v9, v37, v9, s26
	v_and_or_b32 v8, v9, s27, v8
	v_bfe_u32 v9, v39, 16, 1
	v_add3_u32 v9, v39, v9, s26
	v_lshrrev_b32_e32 v9, 16, v9
	v_and_or_b32 v9, v10, s27, v9
	v_or_b32_e32 v10, s33, v24
	v_mul_u32_u24_e32 v10, 0x1600, v10
	v_lshlrev_b32_e32 v10, 1, v10
	v_mov_b32_e32 v11, v3
	ds_read2_b32 v[14:15], v23 offset0:16 offset1:24
	v_lshl_add_u64 v[10:11], v[12:13], 0, v[10:11]
	global_store_dwordx4 v[10:11], v[6:9], off sc1
	ds_read2_b32 v[10:11], v23 offset0:49 offset1:57
	ds_read2_b32 v[16:17], v23 offset0:82 offset1:90
	ds_read2_b32 v[18:19], v23 offset0:115 offset1:123
	s_waitcnt lgkmcnt(3)
	v_bfe_u32 v6, v14, 16, 1
	v_add3_u32 v6, v14, v6, s26
	s_waitcnt lgkmcnt(2)
	v_bfe_u32 v7, v10, 16, 1
	ds_read2_b32 v[20:21], v23 offset0:148 offset1:156
	v_lshrrev_b32_e32 v6, 16, v6
	v_add3_u32 v7, v10, v7, s26
	ds_read2_b32 v[36:37], v23 offset0:181 offset1:189
	v_and_or_b32 v6, v7, s27, v6
	s_waitcnt lgkmcnt(3)
	v_bfe_u32 v7, v16, 16, 1
	v_add3_u32 v7, v16, v7, s26
	s_waitcnt lgkmcnt(2)
	v_bfe_u32 v8, v18, 16, 1
	ds_read2_b32 v[38:39], v23 offset0:214 offset1:222
	v_lshrrev_b32_e32 v7, 16, v7
	v_add3_u32 v8, v18, v8, s26
	ds_read2_b32 v[40:41], v23 offset0:247 offset1:255
	v_and_or_b32 v7, v8, s27, v7
	s_waitcnt lgkmcnt(3)
	v_bfe_u32 v8, v20, 16, 1
	v_add3_u32 v8, v20, v8, s26
	s_waitcnt lgkmcnt(2)
	v_bfe_u32 v9, v36, 16, 1
	v_lshrrev_b32_e32 v8, 16, v8
	v_add3_u32 v9, v36, v9, s26
	v_and_or_b32 v8, v9, s27, v8
	s_waitcnt lgkmcnt(1)
	v_bfe_u32 v9, v38, 16, 1
	v_add3_u32 v9, v38, v9, s26
	s_waitcnt lgkmcnt(0)
	v_bfe_u32 v10, v40, 16, 1
	v_lshrrev_b32_e32 v9, 16, v9
	v_add3_u32 v10, v40, v10, s26
	v_and_or_b32 v9, v10, s27, v9
	v_or_b32_e32 v10, s33, v25
	v_mul_u32_u24_e32 v10, 0x1600, v10
	v_lshlrev_b32_e32 v42, 1, v10
	v_mov_b32_e32 v43, v3
	v_lshl_add_u64 v[42:43], v[12:13], 0, v[42:43]
	global_store_dwordx4 v[42:43], v[6:9], off sc1
	v_bfe_u32 v10, v41, 16, 1
	v_add3_u32 v10, v41, v10, s26
	v_bfe_u32 v6, v15, 16, 1
	v_add3_u32 v6, v15, v6, s26
	v_bfe_u32 v7, v11, 16, 1
	v_lshrrev_b32_e32 v6, 16, v6
	v_add3_u32 v7, v11, v7, s26
	v_and_or_b32 v6, v7, s27, v6
	v_bfe_u32 v7, v17, 16, 1
	v_add3_u32 v7, v17, v7, s26
	v_bfe_u32 v8, v19, 16, 1
	v_lshrrev_b32_e32 v7, 16, v7
	v_add3_u32 v8, v19, v8, s26
	v_and_or_b32 v7, v8, s27, v7
	v_bfe_u32 v8, v21, 16, 1
	v_add3_u32 v8, v21, v8, s26
	v_bfe_u32 v9, v37, 16, 1
	v_lshrrev_b32_e32 v8, 16, v8
	v_add3_u32 v9, v37, v9, s26
	v_and_or_b32 v8, v9, s27, v8
	v_bfe_u32 v9, v39, 16, 1
	v_add3_u32 v9, v39, v9, s26
	v_lshrrev_b32_e32 v9, 16, v9
	v_and_or_b32 v9, v10, s27, v9
	v_or_b32_e32 v10, s33, v26
	v_mul_u32_u24_e32 v10, 0x1600, v10
	v_lshlrev_b32_e32 v10, 1, v10
	v_mov_b32_e32 v11, v3
	v_lshl_add_u64 v[10:11], v[12:13], 0, v[10:11]
	global_store_dwordx4 v[10:11], v[6:9], off sc1
	s_waitcnt lgkmcnt(0)
	s_mov_b64 s[20:21], 0

.LBB0_24:
	v_lshl_add_u64 v[36:37], v[20:21], 0, s[20:21]
	v_lshl_add_u64 v[38:39], v[18:19], 0, s[20:21]
	v_lshl_add_u64 v[40:41], v[16:17], 0, s[20:21]
	v_lshl_add_u64 v[42:43], v[14:15], 0, s[20:21]
	v_lshl_add_u64 v[44:45], v[12:13], 0, s[20:21]
	v_lshl_add_u64 v[46:47], v[10:11], 0, s[20:21]
	v_lshl_add_u64 v[48:49], v[8:9], 0, s[20:21]
	v_lshl_add_u64 v[50:51], v[6:7], 0, s[20:21]
	global_load_dword v52, v[36:37], off nt
	global_load_dword v53, v[38:39], off nt
	global_load_dword v54, v[40:41], off nt
	global_load_dword v55, v[42:43], off nt
	global_load_dword v56, v[44:45], off nt
	global_load_dword v57, v[46:47], off nt
	global_load_dword v58, v[48:49], off nt
	global_load_dword v59, v[50:51], off nt
	s_add_u32 s20, s20, 0x58000
	s_addc_u32 s21, s21, 0
	v_lshl_add_u64 v[36:37], v[20:21], 0, s[20:21]
	v_lshl_add_u64 v[38:39], v[18:19], 0, s[20:21]
	v_lshl_add_u64 v[40:41], v[16:17], 0, s[20:21]
	v_lshl_add_u64 v[42:43], v[14:15], 0, s[20:21]
	v_lshl_add_u64 v[44:45], v[12:13], 0, s[20:21]
	v_lshl_add_u64 v[46:47], v[10:11], 0, s[20:21]
	v_lshl_add_u64 v[48:49], v[8:9], 0, s[20:21]
	v_lshl_add_u64 v[50:51], v[6:7], 0, s[20:21]
	global_load_dword v60, v[36:37], off nt
	global_load_dword v61, v[38:39], off nt
	global_load_dword v62, v[40:41], off nt
	global_load_dword v63, v[42:43], off nt
	global_load_dword v64, v[44:45], off nt
	global_load_dword v65, v[46:47], off nt
	global_load_dword v66, v[48:49], off nt
	global_load_dword v67, v[50:51], off nt
	s_add_u32 s20, s20, 0x58000
	s_addc_u32 s21, s21, 0
	v_lshl_add_u64 v[36:37], v[20:21], 0, s[20:21]
	v_lshl_add_u64 v[38:39], v[18:19], 0, s[20:21]
	v_lshl_add_u64 v[40:41], v[16:17], 0, s[20:21]
	v_lshl_add_u64 v[42:43], v[14:15], 0, s[20:21]
	v_lshl_add_u64 v[44:45], v[12:13], 0, s[20:21]
	v_lshl_add_u64 v[46:47], v[10:11], 0, s[20:21]
	v_lshl_add_u64 v[48:49], v[8:9], 0, s[20:21]
	v_lshl_add_u64 v[50:51], v[6:7], 0, s[20:21]
	global_load_dword v68, v[36:37], off nt
	global_load_dword v69, v[38:39], off nt
	global_load_dword v70, v[40:41], off nt
	global_load_dword v71, v[42:43], off nt
	global_load_dword v72, v[44:45], off nt
	global_load_dword v73, v[46:47], off nt
	global_load_dword v74, v[48:49], off nt
	global_load_dword v75, v[50:51], off nt
	s_add_u32 s20, s20, 0x58000
	s_addc_u32 s21, s21, 0
	v_lshl_add_u64 v[36:37], v[20:21], 0, s[20:21]
	v_lshl_add_u64 v[38:39], v[18:19], 0, s[20:21]
	v_lshl_add_u64 v[40:41], v[16:17], 0, s[20:21]
	v_lshl_add_u64 v[42:43], v[14:15], 0, s[20:21]
	v_lshl_add_u64 v[44:45], v[12:13], 0, s[20:21]
	v_lshl_add_u64 v[46:47], v[10:11], 0, s[20:21]
	v_lshl_add_u64 v[48:49], v[8:9], 0, s[20:21]
	v_lshl_add_u64 v[50:51], v[6:7], 0, s[20:21]
	global_load_dword v76, v[36:37], off nt
	global_load_dword v77, v[38:39], off nt
	global_load_dword v78, v[40:41], off nt
	global_load_dword v79, v[42:43], off nt
	global_load_dword v80, v[44:45], off nt
	global_load_dword v81, v[46:47], off nt
	global_load_dword v82, v[48:49], off nt
	global_load_dword v83, v[50:51], off nt
	s_add_u32 s20, s20, 0x58000
	s_addc_u32 s21, s21, 0
	v_add_u32_e32 v36, 0x400, v35
	s_waitcnt vmcnt(30)
	ds_write2_b32 v35, v52, v53 offset1:66
	s_waitcnt vmcnt(28)
	ds_write2_b32 v35, v54, v55 offset0:132 offset1:198
	s_waitcnt vmcnt(26)
	ds_write2_b32 v36, v56, v57 offset0:8 offset1:74
	s_waitcnt vmcnt(24)
	ds_write2_b32 v36, v58, v59 offset0:140 offset1:206
	v_add_u32_e32 v35, 0x840, v35
	v_add_u32_e32 v36, 0x400, v35
	s_waitcnt vmcnt(22)
	ds_write2_b32 v35, v60, v61 offset1:66
	s_waitcnt vmcnt(20)
	ds_write2_b32 v35, v62, v63 offset0:132 offset1:198
	s_waitcnt vmcnt(18)
	ds_write2_b32 v36, v64, v65 offset0:8 offset1:74
	s_waitcnt vmcnt(16)
	ds_write2_b32 v36, v66, v67 offset0:140 offset1:206
	v_add_u32_e32 v35, 0x840, v35
	v_add_u32_e32 v36, 0x400, v35
	s_waitcnt vmcnt(14)
	ds_write2_b32 v35, v68, v69 offset1:66
	s_waitcnt vmcnt(12)
	ds_write2_b32 v35, v70, v71 offset0:132 offset1:198
	s_waitcnt vmcnt(10)
	ds_write2_b32 v36, v72, v73 offset0:8 offset1:74
	s_waitcnt vmcnt(8)
	ds_write2_b32 v36, v74, v75 offset0:140 offset1:206
	v_add_u32_e32 v35, 0x840, v35
	v_add_u32_e32 v36, 0x400, v35
	s_waitcnt vmcnt(6)
	ds_write2_b32 v35, v76, v77 offset1:66
	s_waitcnt vmcnt(4)
	ds_write2_b32 v35, v78, v79 offset0:132 offset1:198
	s_waitcnt vmcnt(2)
	ds_write2_b32 v36, v80, v81 offset0:8 offset1:74
	s_waitcnt vmcnt(0)
	ds_write2_b32 v36, v82, v83 offset0:140 offset1:206
	v_add_u32_e32 v35, 0x840, v35
	s_lshl_b32 s20, s33, 5
	s_lshl_b32 s21, s33, 6
	s_and_b32 s21, s21, 0x3f00
	s_and_b32 s20, s20, 0x60
	s_waitcnt lgkmcnt(0)
	s_or_b32 s20, s21, s20
	s_or_b32 s33, s20, 0x80
	s_and_b32 s20, 0xffff, s23
	ds_read2_b32 v[10:11], v23 offset1:8
	s_lshl_b32 s20, s20, 1
	ds_read2_b32 v[14:15], v23 offset0:33 offset1:41
	s_add_u32 s20, s30, s20
	s_addc_u32 s21, s31, 0
	ds_read2_b32 v[16:17], v23 offset0:66 offset1:74
	v_lshl_add_u64 v[6:7], s[20:21], 0, v[2:3]
	ds_read2_b32 v[18:19], v23 offset0:99 offset1:107
	v_lshl_add_u64 v[12:13], v[6:7], 0, s[6:7]
	s_waitcnt lgkmcnt(3)
	v_bfe_u32 v6, v10, 16, 1
	v_add3_u32 v6, v10, v6, s26
	s_waitcnt lgkmcnt(2)
	v_bfe_u32 v7, v14, 16, 1
	ds_read2_b32 v[20:21], v23 offset0:132 offset1:140
	v_lshrrev_b32_e32 v6, 16, v6
	v_add3_u32 v7, v14, v7, s26
	ds_read2_b32 v[36:37], v23 offset0:165 offset1:173
	v_and_or_b32 v6, v7, s27, v6
	s_waitcnt lgkmcnt(3)
	v_bfe_u32 v7, v16, 16, 1
	v_add3_u32 v7, v16, v7, s26
	s_waitcnt lgkmcnt(2)
	v_bfe_u32 v8, v18, 16, 1
	ds_read2_b32 v[38:39], v23 offset0:198 offset1:206
	v_lshrrev_b32_e32 v7, 16, v7
	v_add3_u32 v8, v18, v8, s26
	ds_read2_b32 v[40:41], v23 offset0:231 offset1:239
	v_and_or_b32 v7, v8, s27, v7
	s_waitcnt lgkmcnt(3)
	v_bfe_u32 v8, v20, 16, 1
	v_add3_u32 v8, v20, v8, s26
	s_waitcnt lgkmcnt(2)
	v_bfe_u32 v9, v36, 16, 1
	v_lshrrev_b32_e32 v8, 16, v8
	v_add3_u32 v9, v36, v9, s26
	v_and_or_b32 v8, v9, s27, v8
	s_waitcnt lgkmcnt(1)
	v_bfe_u32 v9, v38, 16, 1
	v_add3_u32 v9, v38, v9, s26
	s_waitcnt lgkmcnt(0)
	v_bfe_u32 v10, v40, 16, 1
	v_lshrrev_b32_e32 v9, 16, v9
	v_add3_u32 v10, v40, v10, s26
	v_and_or_b32 v9, v10, s27, v9
	v_or_b32_e32 v10, s33, v22
	v_lshlrev_b32_e32 v42, 12, v10
	v_mov_b32_e32 v43, v3
	v_lshl_add_u64 v[42:43], v[12:13], 0, v[42:43]
	global_store_dwordx4 v[42:43], v[6:9], off sc1
	v_bfe_u32 v10, v41, 16, 1
	v_add3_u32 v10, v41, v10, s26
	v_bfe_u32 v6, v11, 16, 1
	v_add3_u32 v6, v11, v6, s26
	v_bfe_u32 v7, v15, 16, 1
	v_lshrrev_b32_e32 v6, 16, v6
	v_add3_u32 v7, v15, v7, s26
	v_and_or_b32 v6, v7, s27, v6
	v_bfe_u32 v7, v17, 16, 1
	v_add3_u32 v7, v17, v7, s26
	v_bfe_u32 v8, v19, 16, 1
	v_lshrrev_b32_e32 v7, 16, v7
	v_add3_u32 v8, v19, v8, s26
	v_and_or_b32 v7, v8, s27, v7
	v_bfe_u32 v8, v21, 16, 1
	v_add3_u32 v8, v21, v8, s26
	v_bfe_u32 v9, v37, 16, 1
	v_lshrrev_b32_e32 v8, 16, v8
	v_add3_u32 v9, v37, v9, s26
	v_and_or_b32 v8, v9, s27, v8
	v_bfe_u32 v9, v39, 16, 1
	v_add3_u32 v9, v39, v9, s26
	v_lshrrev_b32_e32 v9, 16, v9
	v_and_or_b32 v9, v10, s27, v9
	v_or_b32_e32 v10, s33, v24
	v_lshlrev_b32_e32 v10, 12, v10
	v_mov_b32_e32 v11, v3
	ds_read2_b32 v[14:15], v23 offset0:16 offset1:24
	v_lshl_add_u64 v[10:11], v[12:13], 0, v[10:11]
	global_store_dwordx4 v[10:11], v[6:9], off sc1
	ds_read2_b32 v[10:11], v23 offset0:49 offset1:57
	ds_read2_b32 v[16:17], v23 offset0:82 offset1:90
	ds_read2_b32 v[18:19], v23 offset0:115 offset1:123
	s_waitcnt lgkmcnt(3)
	v_bfe_u32 v6, v14, 16, 1
	v_add3_u32 v6, v14, v6, s26
	s_waitcnt lgkmcnt(2)
	v_bfe_u32 v7, v10, 16, 1
	ds_read2_b32 v[20:21], v23 offset0:148 offset1:156
	v_lshrrev_b32_e32 v6, 16, v6
	v_add3_u32 v7, v10, v7, s26
	ds_read2_b32 v[36:37], v23 offset0:181 offset1:189
	v_and_or_b32 v6, v7, s27, v6
	s_waitcnt lgkmcnt(3)
	v_bfe_u32 v7, v16, 16, 1
	v_add3_u32 v7, v16, v7, s26
	s_waitcnt lgkmcnt(2)
	v_bfe_u32 v8, v18, 16, 1
	ds_read2_b32 v[38:39], v23 offset0:214 offset1:222
	v_lshrrev_b32_e32 v7, 16, v7
	v_add3_u32 v8, v18, v8, s26
	ds_read2_b32 v[40:41], v23 offset0:247 offset1:255
	v_and_or_b32 v7, v8, s27, v7
	s_waitcnt lgkmcnt(3)
	v_bfe_u32 v8, v20, 16, 1
	v_add3_u32 v8, v20, v8, s26
	s_waitcnt lgkmcnt(2)
	v_bfe_u32 v9, v36, 16, 1
	v_lshrrev_b32_e32 v8, 16, v8
	v_add3_u32 v9, v36, v9, s26
	v_and_or_b32 v8, v9, s27, v8
	s_waitcnt lgkmcnt(1)
	v_bfe_u32 v9, v38, 16, 1
	v_add3_u32 v9, v38, v9, s26
	s_waitcnt lgkmcnt(0)
	v_bfe_u32 v10, v40, 16, 1
	v_lshrrev_b32_e32 v9, 16, v9
	v_add3_u32 v10, v40, v10, s26
	v_and_or_b32 v9, v10, s27, v9
	v_or_b32_e32 v10, s33, v25
	v_lshlrev_b32_e32 v42, 12, v10
	v_mov_b32_e32 v43, v3
	v_lshl_add_u64 v[42:43], v[12:13], 0, v[42:43]
	global_store_dwordx4 v[42:43], v[6:9], off sc1
	v_bfe_u32 v10, v41, 16, 1
	v_add3_u32 v10, v41, v10, s26
	v_bfe_u32 v6, v15, 16, 1
	v_add3_u32 v6, v15, v6, s26
	v_bfe_u32 v7, v11, 16, 1
	v_lshrrev_b32_e32 v6, 16, v6
	v_add3_u32 v7, v11, v7, s26
	v_and_or_b32 v6, v7, s27, v6
	v_bfe_u32 v7, v17, 16, 1
	v_add3_u32 v7, v17, v7, s26
	v_bfe_u32 v8, v19, 16, 1
	v_lshrrev_b32_e32 v7, 16, v7
	v_add3_u32 v8, v19, v8, s26
	v_and_or_b32 v7, v8, s27, v7
	v_bfe_u32 v8, v21, 16, 1
	v_add3_u32 v8, v21, v8, s26
	v_bfe_u32 v9, v37, 16, 1
	v_lshrrev_b32_e32 v8, 16, v8
	v_add3_u32 v9, v37, v9, s26
	v_and_or_b32 v8, v9, s27, v8
	v_bfe_u32 v9, v39, 16, 1
	v_add3_u32 v9, v39, v9, s26
	v_lshrrev_b32_e32 v9, 16, v9
	v_and_or_b32 v9, v10, s27, v9
	v_or_b32_e32 v10, s33, v26
	v_lshlrev_b32_e32 v10, 12, v10
	v_mov_b32_e32 v11, v3
	v_lshl_add_u64 v[10:11], v[12:13], 0, v[10:11]
	global_store_dwordx4 v[10:11], v[6:9], off sc1
	s_waitcnt lgkmcnt(0)

.LBB0_29:
	v_lshl_add_u64 v[36:37], v[20:21], 0, s[20:21]
	v_lshl_add_u64 v[38:39], v[18:19], 0, s[20:21]
	v_lshl_add_u64 v[40:41], v[16:17], 0, s[20:21]
	v_lshl_add_u64 v[42:43], v[14:15], 0, s[20:21]
	v_lshl_add_u64 v[44:45], v[12:13], 0, s[20:21]
	v_lshl_add_u64 v[46:47], v[10:11], 0, s[20:21]
	v_lshl_add_u64 v[48:49], v[8:9], 0, s[20:21]
	v_lshl_add_u64 v[50:51], v[6:7], 0, s[20:21]
	global_load_dword v52, v[36:37], off nt
	global_load_dword v53, v[38:39], off nt
	global_load_dword v54, v[40:41], off nt
	global_load_dword v55, v[42:43], off nt
	global_load_dword v56, v[44:45], off nt
	global_load_dword v57, v[46:47], off nt
	global_load_dword v58, v[48:49], off nt
	global_load_dword v59, v[50:51], off nt
	s_add_u32 s20, s20, 0x58000
	s_addc_u32 s21, s21, 0
	v_lshl_add_u64 v[36:37], v[20:21], 0, s[20:21]
	v_lshl_add_u64 v[38:39], v[18:19], 0, s[20:21]
	v_lshl_add_u64 v[40:41], v[16:17], 0, s[20:21]
	v_lshl_add_u64 v[42:43], v[14:15], 0, s[20:21]
	v_lshl_add_u64 v[44:45], v[12:13], 0, s[20:21]
	v_lshl_add_u64 v[46:47], v[10:11], 0, s[20:21]
	v_lshl_add_u64 v[48:49], v[8:9], 0, s[20:21]
	v_lshl_add_u64 v[50:51], v[6:7], 0, s[20:21]
	global_load_dword v60, v[36:37], off nt
	global_load_dword v61, v[38:39], off nt
	global_load_dword v62, v[40:41], off nt
	global_load_dword v63, v[42:43], off nt
	global_load_dword v64, v[44:45], off nt
	global_load_dword v65, v[46:47], off nt
	global_load_dword v66, v[48:49], off nt
	global_load_dword v67, v[50:51], off nt
	s_add_u32 s20, s20, 0x58000
	s_addc_u32 s21, s21, 0
	v_lshl_add_u64 v[36:37], v[20:21], 0, s[20:21]
	v_lshl_add_u64 v[38:39], v[18:19], 0, s[20:21]
	v_lshl_add_u64 v[40:41], v[16:17], 0, s[20:21]
	v_lshl_add_u64 v[42:43], v[14:15], 0, s[20:21]
	v_lshl_add_u64 v[44:45], v[12:13], 0, s[20:21]
	v_lshl_add_u64 v[46:47], v[10:11], 0, s[20:21]
	v_lshl_add_u64 v[48:49], v[8:9], 0, s[20:21]
	v_lshl_add_u64 v[50:51], v[6:7], 0, s[20:21]
	global_load_dword v68, v[36:37], off nt
	global_load_dword v69, v[38:39], off nt
	global_load_dword v70, v[40:41], off nt
	global_load_dword v71, v[42:43], off nt
	global_load_dword v72, v[44:45], off nt
	global_load_dword v73, v[46:47], off nt
	global_load_dword v74, v[48:49], off nt
	global_load_dword v75, v[50:51], off nt
	s_add_u32 s20, s20, 0x58000
	s_addc_u32 s21, s21, 0
	v_lshl_add_u64 v[36:37], v[20:21], 0, s[20:21]
	v_lshl_add_u64 v[38:39], v[18:19], 0, s[20:21]
	v_lshl_add_u64 v[40:41], v[16:17], 0, s[20:21]
	v_lshl_add_u64 v[42:43], v[14:15], 0, s[20:21]
	v_lshl_add_u64 v[44:45], v[12:13], 0, s[20:21]
	v_lshl_add_u64 v[46:47], v[10:11], 0, s[20:21]
	v_lshl_add_u64 v[48:49], v[8:9], 0, s[20:21]
	v_lshl_add_u64 v[50:51], v[6:7], 0, s[20:21]
	global_load_dword v76, v[36:37], off nt
	global_load_dword v77, v[38:39], off nt
	global_load_dword v78, v[40:41], off nt
	global_load_dword v79, v[42:43], off nt
	global_load_dword v80, v[44:45], off nt
	global_load_dword v81, v[46:47], off nt
	global_load_dword v82, v[48:49], off nt
	global_load_dword v83, v[50:51], off nt
	s_add_u32 s20, s20, 0x58000
	s_addc_u32 s21, s21, 0
	v_add_u32_e32 v36, 0x400, v35
	s_waitcnt vmcnt(30)
	ds_write2_b32 v35, v52, v53 offset1:66
	s_waitcnt vmcnt(28)
	ds_write2_b32 v35, v54, v55 offset0:132 offset1:198
	s_waitcnt vmcnt(26)
	ds_write2_b32 v36, v56, v57 offset0:8 offset1:74
	s_waitcnt vmcnt(24)
	ds_write2_b32 v36, v58, v59 offset0:140 offset1:206
	v_add_u32_e32 v35, 0x840, v35
	v_add_u32_e32 v36, 0x400, v35
	s_waitcnt vmcnt(22)
	ds_write2_b32 v35, v60, v61 offset1:66
	s_waitcnt vmcnt(20)
	ds_write2_b32 v35, v62, v63 offset0:132 offset1:198
	s_waitcnt vmcnt(18)
	ds_write2_b32 v36, v64, v65 offset0:8 offset1:74
	s_waitcnt vmcnt(16)
	ds_write2_b32 v36, v66, v67 offset0:140 offset1:206
	v_add_u32_e32 v35, 0x840, v35
	v_add_u32_e32 v36, 0x400, v35
	s_waitcnt vmcnt(14)
	ds_write2_b32 v35, v68, v69 offset1:66
	s_waitcnt vmcnt(12)
	ds_write2_b32 v35, v70, v71 offset0:132 offset1:198
	s_waitcnt vmcnt(10)
	ds_write2_b32 v36, v72, v73 offset0:8 offset1:74
	s_waitcnt vmcnt(8)
	ds_write2_b32 v36, v74, v75 offset0:140 offset1:206
	v_add_u32_e32 v35, 0x840, v35
	v_add_u32_e32 v36, 0x400, v35
	s_waitcnt vmcnt(6)
	ds_write2_b32 v35, v76, v77 offset1:66
	s_waitcnt vmcnt(4)
	ds_write2_b32 v35, v78, v79 offset0:132 offset1:198
	s_waitcnt vmcnt(2)
	ds_write2_b32 v36, v80, v81 offset0:8 offset1:74
	s_waitcnt vmcnt(0)
	ds_write2_b32 v36, v82, v83 offset0:140 offset1:206
	v_add_u32_e32 v35, 0x840, v35
	s_lshl_b32 s20, s33, 5
	s_lshl_b32 s21, s33, 6
	s_waitcnt lgkmcnt(0)
	s_and_b32 s21, s21, 0x3f00
	s_and_b32 s20, s20, 0x60
	s_or_b32 s33, s20, s21
	s_and_b32 s20, 0xffff, s23
	ds_read2_b32 v[10:11], v23 offset1:8
	s_lshl_b32 s20, s20, 1
	ds_read2_b32 v[14:15], v23 offset0:33 offset1:41
	s_add_u32 s20, s30, s20
	s_addc_u32 s21, s31, 0
	ds_read2_b32 v[16:17], v23 offset0:66 offset1:74
	v_lshl_add_u64 v[6:7], s[20:21], 0, v[2:3]
	ds_read2_b32 v[18:19], v23 offset0:99 offset1:107
	v_lshl_add_u64 v[12:13], v[6:7], 0, s[6:7]
	s_waitcnt lgkmcnt(3)
	v_bfe_u32 v6, v10, 16, 1
	v_add3_u32 v6, v10, v6, s26
	s_waitcnt lgkmcnt(2)
	v_bfe_u32 v7, v14, 16, 1
	ds_read2_b32 v[20:21], v23 offset0:132 offset1:140
	v_lshrrev_b32_e32 v6, 16, v6
	v_add3_u32 v7, v14, v7, s26
	ds_read2_b32 v[36:37], v23 offset0:165 offset1:173
	v_and_or_b32 v6, v7, s27, v6
	s_waitcnt lgkmcnt(3)
	v_bfe_u32 v7, v16, 16, 1
	v_add3_u32 v7, v16, v7, s26
	s_waitcnt lgkmcnt(2)
	v_bfe_u32 v8, v18, 16, 1
	ds_read2_b32 v[38:39], v23 offset0:198 offset1:206
	v_lshrrev_b32_e32 v7, 16, v7
	v_add3_u32 v8, v18, v8, s26
	ds_read2_b32 v[40:41], v23 offset0:231 offset1:239
	v_and_or_b32 v7, v8, s27, v7
	s_waitcnt lgkmcnt(3)
	v_bfe_u32 v8, v20, 16, 1
	v_add3_u32 v8, v20, v8, s26
	s_waitcnt lgkmcnt(2)
	v_bfe_u32 v9, v36, 16, 1
	v_lshrrev_b32_e32 v8, 16, v8
	v_add3_u32 v9, v36, v9, s26
	v_and_or_b32 v8, v9, s27, v8
	s_waitcnt lgkmcnt(1)
	v_bfe_u32 v9, v38, 16, 1
	v_add3_u32 v9, v38, v9, s26
	s_waitcnt lgkmcnt(0)
	v_bfe_u32 v10, v40, 16, 1
	v_lshrrev_b32_e32 v9, 16, v9
	v_add3_u32 v10, v40, v10, s26
	v_and_or_b32 v9, v10, s27, v9
	v_or_b32_e32 v10, s33, v22
	v_lshlrev_b32_e32 v42, 12, v10
	v_mov_b32_e32 v43, v3
	v_lshl_add_u64 v[42:43], v[12:13], 0, v[42:43]
	global_store_dwordx4 v[42:43], v[6:9], off sc1
	v_bfe_u32 v10, v41, 16, 1
	v_add3_u32 v10, v41, v10, s26
	v_bfe_u32 v6, v11, 16, 1
	v_add3_u32 v6, v11, v6, s26
	v_bfe_u32 v7, v15, 16, 1
	v_lshrrev_b32_e32 v6, 16, v6
	v_add3_u32 v7, v15, v7, s26
	v_and_or_b32 v6, v7, s27, v6
	v_bfe_u32 v7, v17, 16, 1
	v_add3_u32 v7, v17, v7, s26
	v_bfe_u32 v8, v19, 16, 1
	v_lshrrev_b32_e32 v7, 16, v7
	v_add3_u32 v8, v19, v8, s26
	v_and_or_b32 v7, v8, s27, v7
	v_bfe_u32 v8, v21, 16, 1
	v_add3_u32 v8, v21, v8, s26
	v_bfe_u32 v9, v37, 16, 1
	v_lshrrev_b32_e32 v8, 16, v8
	v_add3_u32 v9, v37, v9, s26
	v_and_or_b32 v8, v9, s27, v8
	v_bfe_u32 v9, v39, 16, 1
	v_add3_u32 v9, v39, v9, s26
	v_lshrrev_b32_e32 v9, 16, v9
	v_and_or_b32 v9, v10, s27, v9
	v_or_b32_e32 v10, s33, v24
	v_lshlrev_b32_e32 v10, 12, v10
	v_mov_b32_e32 v11, v3
	ds_read2_b32 v[14:15], v23 offset0:16 offset1:24
	v_lshl_add_u64 v[10:11], v[12:13], 0, v[10:11]
	global_store_dwordx4 v[10:11], v[6:9], off sc1
	ds_read2_b32 v[10:11], v23 offset0:49 offset1:57
	ds_read2_b32 v[16:17], v23 offset0:82 offset1:90
	ds_read2_b32 v[18:19], v23 offset0:115 offset1:123
	s_waitcnt lgkmcnt(3)
	v_bfe_u32 v6, v14, 16, 1
	v_add3_u32 v6, v14, v6, s26
	s_waitcnt lgkmcnt(2)
	v_bfe_u32 v7, v10, 16, 1
	ds_read2_b32 v[20:21], v23 offset0:148 offset1:156
	v_lshrrev_b32_e32 v6, 16, v6
	v_add3_u32 v7, v10, v7, s26
	ds_read2_b32 v[36:37], v23 offset0:181 offset1:189
	v_and_or_b32 v6, v7, s27, v6
	s_waitcnt lgkmcnt(3)
	v_bfe_u32 v7, v16, 16, 1
	v_add3_u32 v7, v16, v7, s26
	s_waitcnt lgkmcnt(2)
	v_bfe_u32 v8, v18, 16, 1
	ds_read2_b32 v[38:39], v23 offset0:214 offset1:222
	v_lshrrev_b32_e32 v7, 16, v7
	v_add3_u32 v8, v18, v8, s26
	ds_read2_b32 v[40:41], v23 offset0:247 offset1:255
	v_and_or_b32 v7, v8, s27, v7
	s_waitcnt lgkmcnt(3)
	v_bfe_u32 v8, v20, 16, 1
	v_add3_u32 v8, v20, v8, s26
	s_waitcnt lgkmcnt(2)
	v_bfe_u32 v9, v36, 16, 1
	v_lshrrev_b32_e32 v8, 16, v8
	v_add3_u32 v9, v36, v9, s26
	v_and_or_b32 v8, v9, s27, v8
	s_waitcnt lgkmcnt(1)
	v_bfe_u32 v9, v38, 16, 1
	v_add3_u32 v9, v38, v9, s26
	s_waitcnt lgkmcnt(0)
	v_bfe_u32 v10, v40, 16, 1
	v_lshrrev_b32_e32 v9, 16, v9
	v_add3_u32 v10, v40, v10, s26
	v_and_or_b32 v9, v10, s27, v9
	v_or_b32_e32 v10, s33, v25
	v_lshlrev_b32_e32 v42, 12, v10
	v_mov_b32_e32 v43, v3
	v_lshl_add_u64 v[42:43], v[12:13], 0, v[42:43]
	global_store_dwordx4 v[42:43], v[6:9], off sc1
	v_bfe_u32 v10, v41, 16, 1
	v_add3_u32 v10, v41, v10, s26
	v_bfe_u32 v6, v15, 16, 1
	v_add3_u32 v6, v15, v6, s26
	v_bfe_u32 v7, v11, 16, 1
	v_lshrrev_b32_e32 v6, 16, v6
	v_add3_u32 v7, v11, v7, s26
	v_and_or_b32 v6, v7, s27, v6
	v_bfe_u32 v7, v17, 16, 1
	v_add3_u32 v7, v17, v7, s26
	v_bfe_u32 v8, v19, 16, 1
	v_lshrrev_b32_e32 v7, 16, v7
	v_add3_u32 v8, v19, v8, s26
	v_and_or_b32 v7, v8, s27, v7
	v_bfe_u32 v8, v21, 16, 1
	v_add3_u32 v8, v21, v8, s26
	v_bfe_u32 v9, v37, 16, 1
	v_lshrrev_b32_e32 v8, 16, v8
	v_add3_u32 v9, v37, v9, s26
	v_and_or_b32 v8, v9, s27, v8
	v_bfe_u32 v9, v39, 16, 1
	v_add3_u32 v9, v39, v9, s26
	v_lshrrev_b32_e32 v9, 16, v9
	v_and_or_b32 v9, v10, s27, v9
	v_or_b32_e32 v10, s33, v26
	v_lshlrev_b32_e32 v10, 12, v10
	v_mov_b32_e32 v11, v3
	v_lshl_add_u64 v[10:11], v[12:13], 0, v[10:11]
	global_store_dwordx4 v[10:11], v[6:9], off sc1
	s_waitcnt lgkmcnt(0)

.LBB0_34:
	v_lshl_add_u64 v[36:37], v[20:21], 0, s[20:21]
	v_lshl_add_u64 v[38:39], v[18:19], 0, s[20:21]
	v_lshl_add_u64 v[40:41], v[16:17], 0, s[20:21]
	v_lshl_add_u64 v[42:43], v[14:15], 0, s[20:21]
	v_lshl_add_u64 v[44:45], v[12:13], 0, s[20:21]
	v_lshl_add_u64 v[46:47], v[10:11], 0, s[20:21]
	v_lshl_add_u64 v[48:49], v[8:9], 0, s[20:21]
	v_lshl_add_u64 v[50:51], v[6:7], 0, s[20:21]
	global_load_dword v52, v[36:37], off nt
	global_load_dword v53, v[38:39], off nt
	global_load_dword v54, v[40:41], off nt
	global_load_dword v55, v[42:43], off nt
	global_load_dword v56, v[44:45], off nt
	global_load_dword v57, v[46:47], off nt
	global_load_dword v58, v[48:49], off nt
	global_load_dword v59, v[50:51], off nt
	s_add_u32 s20, s20, 0x8000
	s_addc_u32 s21, s21, 0
	v_lshl_add_u64 v[36:37], v[20:21], 0, s[20:21]
	v_lshl_add_u64 v[38:39], v[18:19], 0, s[20:21]
	v_lshl_add_u64 v[40:41], v[16:17], 0, s[20:21]
	v_lshl_add_u64 v[42:43], v[14:15], 0, s[20:21]
	v_lshl_add_u64 v[44:45], v[12:13], 0, s[20:21]
	v_lshl_add_u64 v[46:47], v[10:11], 0, s[20:21]
	v_lshl_add_u64 v[48:49], v[8:9], 0, s[20:21]
	v_lshl_add_u64 v[50:51], v[6:7], 0, s[20:21]
	global_load_dword v60, v[36:37], off nt
	global_load_dword v61, v[38:39], off nt
	global_load_dword v62, v[40:41], off nt
	global_load_dword v63, v[42:43], off nt
	global_load_dword v64, v[44:45], off nt
	global_load_dword v65, v[46:47], off nt
	global_load_dword v66, v[48:49], off nt
	global_load_dword v67, v[50:51], off nt
	s_add_u32 s20, s20, 0x8000
	s_addc_u32 s21, s21, 0
	v_lshl_add_u64 v[36:37], v[20:21], 0, s[20:21]
	v_lshl_add_u64 v[38:39], v[18:19], 0, s[20:21]
	v_lshl_add_u64 v[40:41], v[16:17], 0, s[20:21]
	v_lshl_add_u64 v[42:43], v[14:15], 0, s[20:21]
	v_lshl_add_u64 v[44:45], v[12:13], 0, s[20:21]
	v_lshl_add_u64 v[46:47], v[10:11], 0, s[20:21]
	v_lshl_add_u64 v[48:49], v[8:9], 0, s[20:21]
	v_lshl_add_u64 v[50:51], v[6:7], 0, s[20:21]
	global_load_dword v68, v[36:37], off nt
	global_load_dword v69, v[38:39], off nt
	global_load_dword v70, v[40:41], off nt
	global_load_dword v71, v[42:43], off nt
	global_load_dword v72, v[44:45], off nt
	global_load_dword v73, v[46:47], off nt
	global_load_dword v74, v[48:49], off nt
	global_load_dword v75, v[50:51], off nt
	s_add_u32 s20, s20, 0x8000
	s_addc_u32 s21, s21, 0
	v_lshl_add_u64 v[36:37], v[20:21], 0, s[20:21]
	v_lshl_add_u64 v[38:39], v[18:19], 0, s[20:21]
	v_lshl_add_u64 v[40:41], v[16:17], 0, s[20:21]
	v_lshl_add_u64 v[42:43], v[14:15], 0, s[20:21]
	v_lshl_add_u64 v[44:45], v[12:13], 0, s[20:21]
	v_lshl_add_u64 v[46:47], v[10:11], 0, s[20:21]
	v_lshl_add_u64 v[48:49], v[8:9], 0, s[20:21]
	v_lshl_add_u64 v[50:51], v[6:7], 0, s[20:21]
	global_load_dword v76, v[36:37], off nt
	global_load_dword v77, v[38:39], off nt
	global_load_dword v78, v[40:41], off nt
	global_load_dword v79, v[42:43], off nt
	global_load_dword v80, v[44:45], off nt
	global_load_dword v81, v[46:47], off nt
	global_load_dword v82, v[48:49], off nt
	global_load_dword v83, v[50:51], off nt
	s_add_u32 s20, s20, 0x8000
	s_addc_u32 s21, s21, 0
	v_add_u32_e32 v36, 0x400, v35
	s_waitcnt vmcnt(30)
	ds_write2_b32 v35, v52, v53 offset1:66
	s_waitcnt vmcnt(28)
	ds_write2_b32 v35, v54, v55 offset0:132 offset1:198
	s_waitcnt vmcnt(26)
	ds_write2_b32 v36, v56, v57 offset0:8 offset1:74
	s_waitcnt vmcnt(24)
	ds_write2_b32 v36, v58, v59 offset0:140 offset1:206
	v_add_u32_e32 v35, 0x840, v35
	v_add_u32_e32 v36, 0x400, v35
	s_waitcnt vmcnt(22)
	ds_write2_b32 v35, v60, v61 offset1:66
	s_waitcnt vmcnt(20)
	ds_write2_b32 v35, v62, v63 offset0:132 offset1:198
	s_waitcnt vmcnt(18)
	ds_write2_b32 v36, v64, v65 offset0:8 offset1:74
	s_waitcnt vmcnt(16)
	ds_write2_b32 v36, v66, v67 offset0:140 offset1:206
	v_add_u32_e32 v35, 0x840, v35
	v_add_u32_e32 v36, 0x400, v35
	s_waitcnt vmcnt(14)
	ds_write2_b32 v35, v68, v69 offset1:66
	s_waitcnt vmcnt(12)
	ds_write2_b32 v35, v70, v71 offset0:132 offset1:198
	s_waitcnt vmcnt(10)
	ds_write2_b32 v36, v72, v73 offset0:8 offset1:74
	s_waitcnt vmcnt(8)
	ds_write2_b32 v36, v74, v75 offset0:140 offset1:206
	v_add_u32_e32 v35, 0x840, v35
	v_add_u32_e32 v36, 0x400, v35
	s_waitcnt vmcnt(6)
	ds_write2_b32 v35, v76, v77 offset1:66
	s_waitcnt vmcnt(4)
	ds_write2_b32 v35, v78, v79 offset0:132 offset1:198
	s_waitcnt vmcnt(2)
	ds_write2_b32 v36, v80, v81 offset0:8 offset1:74
	s_waitcnt vmcnt(0)
	ds_write2_b32 v36, v82, v83 offset0:140 offset1:206
	v_add_u32_e32 v35, 0x840, v35
	s_waitcnt lgkmcnt(0)
	s_lshl_b32 s20, s22, 5
	ds_read2_b32 v[10:11], v23 offset1:8
	s_and_b32 s33, s20, 0x1e0
	s_lshl_b32 s20, s23, 1
	ds_read2_b32 v[14:15], v23 offset0:33 offset1:41
	s_add_u32 s20, s30, s20
	s_addc_u32 s21, s31, 0
	ds_read2_b32 v[16:17], v23 offset0:66 offset1:74
	v_lshl_add_u64 v[6:7], s[20:21], 0, v[2:3]
	ds_read2_b32 v[18:19], v23 offset0:99 offset1:107
	v_lshl_add_u64 v[12:13], v[6:7], 0, s[38:39]
	s_waitcnt lgkmcnt(3)
	v_bfe_u32 v6, v10, 16, 1
	v_add3_u32 v6, v10, v6, s26
	s_waitcnt lgkmcnt(2)
	v_bfe_u32 v7, v14, 16, 1
	ds_read2_b32 v[20:21], v23 offset0:132 offset1:140
	v_lshrrev_b32_e32 v6, 16, v6
	v_add3_u32 v7, v14, v7, s26
	ds_read2_b32 v[36:37], v23 offset0:165 offset1:173
	v_and_or_b32 v6, v7, s27, v6
	s_waitcnt lgkmcnt(3)
	v_bfe_u32 v7, v16, 16, 1
	v_add3_u32 v7, v16, v7, s26
	s_waitcnt lgkmcnt(2)
	v_bfe_u32 v8, v18, 16, 1
	ds_read2_b32 v[38:39], v23 offset0:198 offset1:206
	v_lshrrev_b32_e32 v7, 16, v7
	v_add3_u32 v8, v18, v8, s26
	ds_read2_b32 v[40:41], v23 offset0:231 offset1:239
	v_and_or_b32 v7, v8, s27, v7
	s_waitcnt lgkmcnt(3)
	v_bfe_u32 v8, v20, 16, 1
	v_add3_u32 v8, v20, v8, s26
	s_waitcnt lgkmcnt(2)
	v_bfe_u32 v9, v36, 16, 1
	v_lshrrev_b32_e32 v8, 16, v8
	v_add3_u32 v9, v36, v9, s26
	v_and_or_b32 v8, v9, s27, v8
	s_waitcnt lgkmcnt(1)
	v_bfe_u32 v9, v38, 16, 1
	v_add3_u32 v9, v38, v9, s26
	s_waitcnt lgkmcnt(0)
	v_bfe_u32 v10, v40, 16, 1
	v_lshrrev_b32_e32 v9, 16, v9
	v_add3_u32 v10, v40, v10, s26
	v_and_or_b32 v9, v10, s27, v9
	v_or_b32_e32 v10, s33, v22
	v_lshlrev_b32_e32 v42, 10, v10
	v_mov_b32_e32 v43, v3
	v_lshl_add_u64 v[42:43], v[12:13], 0, v[42:43]
	global_store_dwordx4 v[42:43], v[6:9], off sc1
	v_bfe_u32 v10, v41, 16, 1
	v_add3_u32 v10, v41, v10, s26
	v_bfe_u32 v6, v11, 16, 1
	v_add3_u32 v6, v11, v6, s26
	v_bfe_u32 v7, v15, 16, 1
	v_lshrrev_b32_e32 v6, 16, v6
	v_add3_u32 v7, v15, v7, s26
	v_and_or_b32 v6, v7, s27, v6
	v_bfe_u32 v7, v17, 16, 1
	v_add3_u32 v7, v17, v7, s26
	v_bfe_u32 v8, v19, 16, 1
	v_lshrrev_b32_e32 v7, 16, v7
	v_add3_u32 v8, v19, v8, s26
	v_and_or_b32 v7, v8, s27, v7
	v_bfe_u32 v8, v21, 16, 1
	v_add3_u32 v8, v21, v8, s26
	v_bfe_u32 v9, v37, 16, 1
	v_lshrrev_b32_e32 v8, 16, v8
	v_add3_u32 v9, v37, v9, s26
	v_and_or_b32 v8, v9, s27, v8
	v_bfe_u32 v9, v39, 16, 1
	v_add3_u32 v9, v39, v9, s26
	v_lshrrev_b32_e32 v9, 16, v9
	v_and_or_b32 v9, v10, s27, v9
	v_or_b32_e32 v10, s33, v24
	v_lshlrev_b32_e32 v10, 10, v10
	v_mov_b32_e32 v11, v3
	ds_read2_b32 v[14:15], v23 offset0:16 offset1:24
	v_lshl_add_u64 v[10:11], v[12:13], 0, v[10:11]
	global_store_dwordx4 v[10:11], v[6:9], off sc1
	ds_read2_b32 v[10:11], v23 offset0:49 offset1:57
	ds_read2_b32 v[16:17], v23 offset0:82 offset1:90
	ds_read2_b32 v[18:19], v23 offset0:115 offset1:123
	s_waitcnt lgkmcnt(3)
	v_bfe_u32 v6, v14, 16, 1
	v_add3_u32 v6, v14, v6, s26
	s_waitcnt lgkmcnt(2)
	v_bfe_u32 v7, v10, 16, 1
	ds_read2_b32 v[20:21], v23 offset0:148 offset1:156
	v_lshrrev_b32_e32 v6, 16, v6
	v_add3_u32 v7, v10, v7, s26
	ds_read2_b32 v[36:37], v23 offset0:181 offset1:189
	v_and_or_b32 v6, v7, s27, v6
	s_waitcnt lgkmcnt(3)
	v_bfe_u32 v7, v16, 16, 1
	v_add3_u32 v7, v16, v7, s26
	s_waitcnt lgkmcnt(2)
	v_bfe_u32 v8, v18, 16, 1
	ds_read2_b32 v[38:39], v23 offset0:214 offset1:222
	v_lshrrev_b32_e32 v7, 16, v7
	v_add3_u32 v8, v18, v8, s26
	ds_read2_b32 v[40:41], v23 offset0:247 offset1:255
	v_and_or_b32 v7, v8, s27, v7
	s_waitcnt lgkmcnt(3)
	v_bfe_u32 v8, v20, 16, 1
	v_add3_u32 v8, v20, v8, s26
	s_waitcnt lgkmcnt(2)
	v_bfe_u32 v9, v36, 16, 1
	v_lshrrev_b32_e32 v8, 16, v8
	v_add3_u32 v9, v36, v9, s26
	v_and_or_b32 v8, v9, s27, v8
	s_waitcnt lgkmcnt(1)
	v_bfe_u32 v9, v38, 16, 1
	v_add3_u32 v9, v38, v9, s26
	s_waitcnt lgkmcnt(0)
	v_bfe_u32 v10, v40, 16, 1
	v_lshrrev_b32_e32 v9, 16, v9
	v_add3_u32 v10, v40, v10, s26
	v_and_or_b32 v9, v10, s27, v9
	v_or_b32_e32 v10, s33, v25
	v_lshlrev_b32_e32 v42, 10, v10
	v_mov_b32_e32 v43, v3
	v_lshl_add_u64 v[42:43], v[12:13], 0, v[42:43]
	global_store_dwordx4 v[42:43], v[6:9], off sc1
	v_bfe_u32 v10, v41, 16, 1
	v_add3_u32 v10, v41, v10, s26
	v_bfe_u32 v6, v15, 16, 1
	v_add3_u32 v6, v15, v6, s26
	v_bfe_u32 v7, v11, 16, 1
	v_lshrrev_b32_e32 v6, 16, v6
	v_add3_u32 v7, v11, v7, s26
	v_and_or_b32 v6, v7, s27, v6
	v_bfe_u32 v7, v17, 16, 1
	v_add3_u32 v7, v17, v7, s26
	v_bfe_u32 v8, v19, 16, 1
	v_lshrrev_b32_e32 v7, 16, v7
	v_add3_u32 v8, v19, v8, s26
	v_and_or_b32 v7, v8, s27, v7
	v_bfe_u32 v8, v21, 16, 1
	v_add3_u32 v8, v21, v8, s26
	v_bfe_u32 v9, v37, 16, 1
	v_lshrrev_b32_e32 v8, 16, v8
	v_add3_u32 v9, v37, v9, s26
	v_and_or_b32 v8, v9, s27, v8
	v_bfe_u32 v9, v39, 16, 1
	v_add3_u32 v9, v39, v9, s26
	v_lshrrev_b32_e32 v9, 16, v9
	v_and_or_b32 v9, v10, s27, v9
	v_or_b32_e32 v10, s33, v26
	v_lshlrev_b32_e32 v10, 10, v10
	v_mov_b32_e32 v11, v3
	v_lshl_add_u64 v[10:11], v[12:13], 0, v[10:11]
	global_store_dwordx4 v[10:11], v[6:9], off sc1
	s_waitcnt lgkmcnt(0)

.LBB0_39:
	v_lshl_add_u64 v[36:37], v[20:21], 0, s[20:21]
	v_lshl_add_u64 v[38:39], v[18:19], 0, s[20:21]
	v_lshl_add_u64 v[40:41], v[16:17], 0, s[20:21]
	v_lshl_add_u64 v[42:43], v[14:15], 0, s[20:21]
	v_lshl_add_u64 v[44:45], v[12:13], 0, s[20:21]
	v_lshl_add_u64 v[46:47], v[10:11], 0, s[20:21]
	v_lshl_add_u64 v[48:49], v[8:9], 0, s[20:21]
	v_lshl_add_u64 v[50:51], v[6:7], 0, s[20:21]
	global_load_dword v52, v[36:37], off nt
	global_load_dword v53, v[38:39], off nt
	global_load_dword v54, v[40:41], off nt
	global_load_dword v55, v[42:43], off nt
	global_load_dword v56, v[44:45], off nt
	global_load_dword v57, v[46:47], off nt
	global_load_dword v58, v[48:49], off nt
	global_load_dword v59, v[50:51], off nt
	s_add_u32 s20, s20, 0x20000
	s_addc_u32 s21, s21, 0
	v_lshl_add_u64 v[36:37], v[20:21], 0, s[20:21]
	v_lshl_add_u64 v[38:39], v[18:19], 0, s[20:21]
	v_lshl_add_u64 v[40:41], v[16:17], 0, s[20:21]
	v_lshl_add_u64 v[42:43], v[14:15], 0, s[20:21]
	v_lshl_add_u64 v[44:45], v[12:13], 0, s[20:21]
	v_lshl_add_u64 v[46:47], v[10:11], 0, s[20:21]
	v_lshl_add_u64 v[48:49], v[8:9], 0, s[20:21]
	v_lshl_add_u64 v[50:51], v[6:7], 0, s[20:21]
	global_load_dword v60, v[36:37], off nt
	global_load_dword v61, v[38:39], off nt
	global_load_dword v62, v[40:41], off nt
	global_load_dword v63, v[42:43], off nt
	global_load_dword v64, v[44:45], off nt
	global_load_dword v65, v[46:47], off nt
	global_load_dword v66, v[48:49], off nt
	global_load_dword v67, v[50:51], off nt
	s_add_u32 s20, s20, 0x20000
	s_addc_u32 s21, s21, 0
	v_lshl_add_u64 v[36:37], v[20:21], 0, s[20:21]
	v_lshl_add_u64 v[38:39], v[18:19], 0, s[20:21]
	v_lshl_add_u64 v[40:41], v[16:17], 0, s[20:21]
	v_lshl_add_u64 v[42:43], v[14:15], 0, s[20:21]
	v_lshl_add_u64 v[44:45], v[12:13], 0, s[20:21]
	v_lshl_add_u64 v[46:47], v[10:11], 0, s[20:21]
	v_lshl_add_u64 v[48:49], v[8:9], 0, s[20:21]
	v_lshl_add_u64 v[50:51], v[6:7], 0, s[20:21]
	global_load_dword v68, v[36:37], off nt
	global_load_dword v69, v[38:39], off nt
	global_load_dword v70, v[40:41], off nt
	global_load_dword v71, v[42:43], off nt
	global_load_dword v72, v[44:45], off nt
	global_load_dword v73, v[46:47], off nt
	global_load_dword v74, v[48:49], off nt
	global_load_dword v75, v[50:51], off nt
	s_add_u32 s20, s20, 0x20000
	s_addc_u32 s21, s21, 0
	v_lshl_add_u64 v[36:37], v[20:21], 0, s[20:21]
	v_lshl_add_u64 v[38:39], v[18:19], 0, s[20:21]
	v_lshl_add_u64 v[40:41], v[16:17], 0, s[20:21]
	v_lshl_add_u64 v[42:43], v[14:15], 0, s[20:21]
	v_lshl_add_u64 v[44:45], v[12:13], 0, s[20:21]
	v_lshl_add_u64 v[46:47], v[10:11], 0, s[20:21]
	v_lshl_add_u64 v[48:49], v[8:9], 0, s[20:21]
	v_lshl_add_u64 v[50:51], v[6:7], 0, s[20:21]
	global_load_dword v76, v[36:37], off nt
	global_load_dword v77, v[38:39], off nt
	global_load_dword v78, v[40:41], off nt
	global_load_dword v79, v[42:43], off nt
	global_load_dword v80, v[44:45], off nt
	global_load_dword v81, v[46:47], off nt
	global_load_dword v82, v[48:49], off nt
	global_load_dword v83, v[50:51], off nt
	s_add_u32 s20, s20, 0x20000
	s_addc_u32 s21, s21, 0
	v_add_u32_e32 v36, 0x400, v35
	s_waitcnt vmcnt(30)
	ds_write2_b32 v35, v52, v53 offset1:66
	s_waitcnt vmcnt(28)
	ds_write2_b32 v35, v54, v55 offset0:132 offset1:198
	s_waitcnt vmcnt(26)
	ds_write2_b32 v36, v56, v57 offset0:8 offset1:74
	s_waitcnt vmcnt(24)
	ds_write2_b32 v36, v58, v59 offset0:140 offset1:206
	v_add_u32_e32 v35, 0x840, v35
	v_add_u32_e32 v36, 0x400, v35
	s_waitcnt vmcnt(22)
	ds_write2_b32 v35, v60, v61 offset1:66
	s_waitcnt vmcnt(20)
	ds_write2_b32 v35, v62, v63 offset0:132 offset1:198
	s_waitcnt vmcnt(18)
	ds_write2_b32 v36, v64, v65 offset0:8 offset1:74
	s_waitcnt vmcnt(16)
	ds_write2_b32 v36, v66, v67 offset0:140 offset1:206
	v_add_u32_e32 v35, 0x840, v35
	v_add_u32_e32 v36, 0x400, v35
	s_waitcnt vmcnt(14)
	ds_write2_b32 v35, v68, v69 offset1:66
	s_waitcnt vmcnt(12)
	ds_write2_b32 v35, v70, v71 offset0:132 offset1:198
	s_waitcnt vmcnt(10)
	ds_write2_b32 v36, v72, v73 offset0:8 offset1:74
	s_waitcnt vmcnt(8)
	ds_write2_b32 v36, v74, v75 offset0:140 offset1:206
	v_add_u32_e32 v35, 0x840, v35
	v_add_u32_e32 v36, 0x400, v35
	s_waitcnt vmcnt(6)
	ds_write2_b32 v35, v76, v77 offset1:66
	s_waitcnt vmcnt(4)
	ds_write2_b32 v35, v78, v79 offset0:132 offset1:198
	s_waitcnt vmcnt(2)
	ds_write2_b32 v36, v80, v81 offset0:8 offset1:74
	s_waitcnt vmcnt(0)
	ds_write2_b32 v36, v82, v83 offset0:140 offset1:206
	v_add_u32_e32 v35, 0x840, v35
	s_waitcnt lgkmcnt(0)
	s_lshl_b32 s20, s22, 5
	ds_read2_b32 v[10:11], v23 offset1:8
	s_and_b32 s23, s20, 0x7e0
	s_lshl_b32 s19, s19, 1
	ds_read2_b32 v[14:15], v23 offset0:33 offset1:41
	s_add_u32 s20, s30, s19
	s_addc_u32 s21, s31, 0
	ds_read2_b32 v[16:17], v23 offset0:66 offset1:74
	v_lshl_add_u64 v[6:7], s[20:21], 0, v[2:3]
	ds_read2_b32 v[18:19], v23 offset0:99 offset1:107
	v_lshl_add_u64 v[12:13], v[6:7], 0, s[12:13]
	s_waitcnt lgkmcnt(3)
	v_bfe_u32 v6, v10, 16, 1
	v_add3_u32 v6, v10, v6, s26
	s_waitcnt lgkmcnt(2)
	v_bfe_u32 v7, v14, 16, 1
	ds_read2_b32 v[20:21], v23 offset0:132 offset1:140
	v_lshrrev_b32_e32 v6, 16, v6
	v_add3_u32 v7, v14, v7, s26
	ds_read2_b32 v[36:37], v23 offset0:165 offset1:173
	v_and_or_b32 v6, v7, s27, v6
	s_waitcnt lgkmcnt(3)
	v_bfe_u32 v7, v16, 16, 1
	v_add3_u32 v7, v16, v7, s26
	s_waitcnt lgkmcnt(2)
	v_bfe_u32 v8, v18, 16, 1
	ds_read2_b32 v[38:39], v23 offset0:198 offset1:206
	v_lshrrev_b32_e32 v7, 16, v7
	v_add3_u32 v8, v18, v8, s26
	ds_read2_b32 v[40:41], v23 offset0:231 offset1:239
	v_and_or_b32 v7, v8, s27, v7
	s_waitcnt lgkmcnt(3)
	v_bfe_u32 v8, v20, 16, 1
	v_add3_u32 v8, v20, v8, s26
	s_waitcnt lgkmcnt(2)
	v_bfe_u32 v9, v36, 16, 1
	v_lshrrev_b32_e32 v8, 16, v8
	v_add3_u32 v9, v36, v9, s26
	v_and_or_b32 v8, v9, s27, v8
	s_waitcnt lgkmcnt(1)
	v_bfe_u32 v9, v38, 16, 1
	v_add3_u32 v9, v38, v9, s26
	s_waitcnt lgkmcnt(0)
	v_bfe_u32 v10, v40, 16, 1
	v_lshrrev_b32_e32 v9, 16, v9
	v_add3_u32 v10, v40, v10, s26
	v_and_or_b32 v9, v10, s27, v9
	v_or_b32_e32 v10, s23, v22
	v_lshlrev_b32_e32 v42, 12, v10
	v_mov_b32_e32 v43, v3
	v_lshl_add_u64 v[42:43], v[12:13], 0, v[42:43]
	global_store_dwordx4 v[42:43], v[6:9], off sc1
	v_bfe_u32 v10, v41, 16, 1
	v_add3_u32 v10, v41, v10, s26
	v_bfe_u32 v6, v11, 16, 1
	v_add3_u32 v6, v11, v6, s26
	v_bfe_u32 v7, v15, 16, 1
	v_lshrrev_b32_e32 v6, 16, v6
	v_add3_u32 v7, v15, v7, s26
	v_and_or_b32 v6, v7, s27, v6
	v_bfe_u32 v7, v17, 16, 1
	v_add3_u32 v7, v17, v7, s26
	v_bfe_u32 v8, v19, 16, 1
	v_lshrrev_b32_e32 v7, 16, v7
	v_add3_u32 v8, v19, v8, s26
	v_and_or_b32 v7, v8, s27, v7
	v_bfe_u32 v8, v21, 16, 1
	v_add3_u32 v8, v21, v8, s26
	v_bfe_u32 v9, v37, 16, 1
	v_lshrrev_b32_e32 v8, 16, v8
	v_add3_u32 v9, v37, v9, s26
	v_and_or_b32 v8, v9, s27, v8
	v_bfe_u32 v9, v39, 16, 1
	v_add3_u32 v9, v39, v9, s26
	v_lshrrev_b32_e32 v9, 16, v9
	v_and_or_b32 v9, v10, s27, v9
	v_or_b32_e32 v10, s23, v24
	v_lshlrev_b32_e32 v10, 12, v10
	v_mov_b32_e32 v11, v3
	ds_read2_b32 v[14:15], v23 offset0:16 offset1:24
	v_lshl_add_u64 v[10:11], v[12:13], 0, v[10:11]
	global_store_dwordx4 v[10:11], v[6:9], off sc1
	ds_read2_b32 v[10:11], v23 offset0:49 offset1:57
	ds_read2_b32 v[16:17], v23 offset0:82 offset1:90
	ds_read2_b32 v[18:19], v23 offset0:115 offset1:123
	s_waitcnt lgkmcnt(3)
	v_bfe_u32 v6, v14, 16, 1
	v_add3_u32 v6, v14, v6, s26
	s_waitcnt lgkmcnt(2)
	v_bfe_u32 v7, v10, 16, 1
	ds_read2_b32 v[20:21], v23 offset0:148 offset1:156
	v_lshrrev_b32_e32 v6, 16, v6
	v_add3_u32 v7, v10, v7, s26
	ds_read2_b32 v[36:37], v23 offset0:181 offset1:189
	v_and_or_b32 v6, v7, s27, v6
	s_waitcnt lgkmcnt(3)
	v_bfe_u32 v7, v16, 16, 1
	v_add3_u32 v7, v16, v7, s26
	s_waitcnt lgkmcnt(2)
	v_bfe_u32 v8, v18, 16, 1
	ds_read2_b32 v[38:39], v23 offset0:214 offset1:222
	v_lshrrev_b32_e32 v7, 16, v7
	v_add3_u32 v8, v18, v8, s26
	ds_read2_b32 v[40:41], v23 offset0:247 offset1:255
	v_and_or_b32 v7, v8, s27, v7
	s_waitcnt lgkmcnt(3)
	v_bfe_u32 v8, v20, 16, 1
	v_add3_u32 v8, v20, v8, s26
	s_waitcnt lgkmcnt(2)
	v_bfe_u32 v9, v36, 16, 1
	v_lshrrev_b32_e32 v8, 16, v8
	v_add3_u32 v9, v36, v9, s26
	v_and_or_b32 v8, v9, s27, v8
	s_waitcnt lgkmcnt(1)
	v_bfe_u32 v9, v38, 16, 1
	v_add3_u32 v9, v38, v9, s26
	s_waitcnt lgkmcnt(0)
	v_bfe_u32 v10, v40, 16, 1
	v_lshrrev_b32_e32 v9, 16, v9
	v_add3_u32 v10, v40, v10, s26
	v_and_or_b32 v9, v10, s27, v9
	v_or_b32_e32 v10, s23, v25
	v_lshlrev_b32_e32 v42, 12, v10
	v_mov_b32_e32 v43, v3
	v_lshl_add_u64 v[42:43], v[12:13], 0, v[42:43]
	global_store_dwordx4 v[42:43], v[6:9], off sc1
	v_bfe_u32 v10, v41, 16, 1
	v_add3_u32 v10, v41, v10, s26
	v_bfe_u32 v6, v15, 16, 1
	v_add3_u32 v6, v15, v6, s26
	v_bfe_u32 v7, v11, 16, 1
	v_lshrrev_b32_e32 v6, 16, v6
	v_add3_u32 v7, v11, v7, s26
	v_and_or_b32 v6, v7, s27, v6
	v_bfe_u32 v7, v17, 16, 1
	v_add3_u32 v7, v17, v7, s26
	v_bfe_u32 v8, v19, 16, 1
	v_lshrrev_b32_e32 v7, 16, v7
	v_add3_u32 v8, v19, v8, s26
	v_and_or_b32 v7, v8, s27, v7
	v_bfe_u32 v8, v21, 16, 1
	v_add3_u32 v8, v21, v8, s26
	v_bfe_u32 v9, v37, 16, 1
	v_lshrrev_b32_e32 v8, 16, v8
	v_add3_u32 v9, v37, v9, s26
	v_and_or_b32 v8, v9, s27, v8
	v_bfe_u32 v9, v39, 16, 1
	v_add3_u32 v9, v39, v9, s26
	v_lshrrev_b32_e32 v9, 16, v9
	v_and_or_b32 v9, v10, s27, v9
	v_or_b32_e32 v10, s23, v26
	v_lshlrev_b32_e32 v10, 12, v10
	v_mov_b32_e32 v11, v3
	v_lshl_add_u64 v[10:11], v[12:13], 0, v[10:11]
	global_store_dwordx4 v[10:11], v[6:9], off sc1
	s_waitcnt lgkmcnt(0)

.LBB0_44:
	v_lshl_add_u64 v[36:37], v[20:21], 0, s[20:21]
	v_lshl_add_u64 v[38:39], v[18:19], 0, s[20:21]
	v_lshl_add_u64 v[40:41], v[16:17], 0, s[20:21]
	v_lshl_add_u64 v[42:43], v[14:15], 0, s[20:21]
	v_lshl_add_u64 v[44:45], v[12:13], 0, s[20:21]
	v_lshl_add_u64 v[46:47], v[10:11], 0, s[20:21]
	v_lshl_add_u64 v[48:49], v[8:9], 0, s[20:21]
	v_lshl_add_u64 v[50:51], v[6:7], 0, s[20:21]
	global_load_dword v52, v[36:37], off nt
	global_load_dword v53, v[38:39], off nt
	global_load_dword v54, v[40:41], off nt
	global_load_dword v55, v[42:43], off nt
	global_load_dword v56, v[44:45], off nt
	global_load_dword v57, v[46:47], off nt
	global_load_dword v58, v[48:49], off nt
	global_load_dword v59, v[50:51], off nt
	s_add_u32 s20, s20, 0x50000
	s_addc_u32 s21, s21, 0
	v_lshl_add_u64 v[36:37], v[20:21], 0, s[20:21]
	v_lshl_add_u64 v[38:39], v[18:19], 0, s[20:21]
	v_lshl_add_u64 v[40:41], v[16:17], 0, s[20:21]
	v_lshl_add_u64 v[42:43], v[14:15], 0, s[20:21]
	v_lshl_add_u64 v[44:45], v[12:13], 0, s[20:21]
	v_lshl_add_u64 v[46:47], v[10:11], 0, s[20:21]
	v_lshl_add_u64 v[48:49], v[8:9], 0, s[20:21]
	v_lshl_add_u64 v[50:51], v[6:7], 0, s[20:21]
	global_load_dword v60, v[36:37], off nt
	global_load_dword v61, v[38:39], off nt
	global_load_dword v62, v[40:41], off nt
	global_load_dword v63, v[42:43], off nt
	global_load_dword v64, v[44:45], off nt
	global_load_dword v65, v[46:47], off nt
	global_load_dword v66, v[48:49], off nt
	global_load_dword v67, v[50:51], off nt
	s_add_u32 s20, s20, 0x50000
	s_addc_u32 s21, s21, 0
	v_lshl_add_u64 v[36:37], v[20:21], 0, s[20:21]
	v_lshl_add_u64 v[38:39], v[18:19], 0, s[20:21]
	v_lshl_add_u64 v[40:41], v[16:17], 0, s[20:21]
	v_lshl_add_u64 v[42:43], v[14:15], 0, s[20:21]
	v_lshl_add_u64 v[44:45], v[12:13], 0, s[20:21]
	v_lshl_add_u64 v[46:47], v[10:11], 0, s[20:21]
	v_lshl_add_u64 v[48:49], v[8:9], 0, s[20:21]
	v_lshl_add_u64 v[50:51], v[6:7], 0, s[20:21]
	global_load_dword v68, v[36:37], off nt
	global_load_dword v69, v[38:39], off nt
	global_load_dword v70, v[40:41], off nt
	global_load_dword v71, v[42:43], off nt
	global_load_dword v72, v[44:45], off nt
	global_load_dword v73, v[46:47], off nt
	global_load_dword v74, v[48:49], off nt
	global_load_dword v75, v[50:51], off nt
	s_add_u32 s20, s20, 0x50000
	s_addc_u32 s21, s21, 0
	v_lshl_add_u64 v[36:37], v[20:21], 0, s[20:21]
	v_lshl_add_u64 v[38:39], v[18:19], 0, s[20:21]
	v_lshl_add_u64 v[40:41], v[16:17], 0, s[20:21]
	v_lshl_add_u64 v[42:43], v[14:15], 0, s[20:21]
	v_lshl_add_u64 v[44:45], v[12:13], 0, s[20:21]
	v_lshl_add_u64 v[46:47], v[10:11], 0, s[20:21]
	v_lshl_add_u64 v[48:49], v[8:9], 0, s[20:21]
	v_lshl_add_u64 v[50:51], v[6:7], 0, s[20:21]
	global_load_dword v76, v[36:37], off nt
	global_load_dword v77, v[38:39], off nt
	global_load_dword v78, v[40:41], off nt
	global_load_dword v79, v[42:43], off nt
	global_load_dword v80, v[44:45], off nt
	global_load_dword v81, v[46:47], off nt
	global_load_dword v82, v[48:49], off nt
	global_load_dword v83, v[50:51], off nt
	s_add_u32 s20, s20, 0x50000
	s_addc_u32 s21, s21, 0
	v_add_u32_e32 v36, 0x400, v35
	s_waitcnt vmcnt(30)
	ds_write2_b32 v35, v52, v53 offset1:66
	s_waitcnt vmcnt(28)
	ds_write2_b32 v35, v54, v55 offset0:132 offset1:198
	s_waitcnt vmcnt(26)
	ds_write2_b32 v36, v56, v57 offset0:8 offset1:74
	s_waitcnt vmcnt(24)
	ds_write2_b32 v36, v58, v59 offset0:140 offset1:206
	v_add_u32_e32 v35, 0x840, v35
	v_add_u32_e32 v36, 0x400, v35
	s_waitcnt vmcnt(22)
	ds_write2_b32 v35, v60, v61 offset1:66
	s_waitcnt vmcnt(20)
	ds_write2_b32 v35, v62, v63 offset0:132 offset1:198
	s_waitcnt vmcnt(18)
	ds_write2_b32 v36, v64, v65 offset0:8 offset1:74
	s_waitcnt vmcnt(16)
	ds_write2_b32 v36, v66, v67 offset0:140 offset1:206
	v_add_u32_e32 v35, 0x840, v35
	v_add_u32_e32 v36, 0x400, v35
	s_waitcnt vmcnt(14)
	ds_write2_b32 v35, v68, v69 offset1:66
	s_waitcnt vmcnt(12)
	ds_write2_b32 v35, v70, v71 offset0:132 offset1:198
	s_waitcnt vmcnt(10)
	ds_write2_b32 v36, v72, v73 offset0:8 offset1:74
	s_waitcnt vmcnt(8)
	ds_write2_b32 v36, v74, v75 offset0:140 offset1:206
	v_add_u32_e32 v35, 0x840, v35
	v_add_u32_e32 v36, 0x400, v35
	s_waitcnt vmcnt(6)
	ds_write2_b32 v35, v76, v77 offset1:66
	s_waitcnt vmcnt(4)
	ds_write2_b32 v35, v78, v79 offset0:132 offset1:198
	s_waitcnt vmcnt(2)
	ds_write2_b32 v36, v80, v81 offset0:8 offset1:74
	s_waitcnt vmcnt(0)
	ds_write2_b32 v36, v82, v83 offset0:140 offset1:206
	v_add_u32_e32 v35, 0x840, v35
	s_waitcnt lgkmcnt(0)
	s_and_b32 s19, 0xffff, s19
	ds_read2_b32 v[10:11], v23 offset1:8
	s_and_b32 s23, 0xffff, s23
	s_lshl_b32 s19, s19, 1
	ds_read2_b32 v[14:15], v23 offset0:33 offset1:41
	s_add_u32 s20, s30, s19
	s_addc_u32 s21, s31, 0
	ds_read2_b32 v[16:17], v23 offset0:66 offset1:74
	v_lshl_add_u64 v[6:7], s[20:21], 0, v[2:3]
	ds_read2_b32 v[18:19], v23 offset0:99 offset1:107
	v_lshl_add_u64 v[12:13], v[6:7], 0, s[14:15]
	s_waitcnt lgkmcnt(3)
	v_bfe_u32 v6, v10, 16, 1
	v_add3_u32 v6, v10, v6, s26
	s_waitcnt lgkmcnt(2)
	v_bfe_u32 v7, v14, 16, 1
	ds_read2_b32 v[20:21], v23 offset0:132 offset1:140
	v_lshrrev_b32_e32 v6, 16, v6
	v_add3_u32 v7, v14, v7, s26
	ds_read2_b32 v[36:37], v23 offset0:165 offset1:173
	v_and_or_b32 v6, v7, s27, v6
	s_waitcnt lgkmcnt(3)
	v_bfe_u32 v7, v16, 16, 1
	v_add3_u32 v7, v16, v7, s26
	s_waitcnt lgkmcnt(2)
	v_bfe_u32 v8, v18, 16, 1
	ds_read2_b32 v[38:39], v23 offset0:198 offset1:206
	v_lshrrev_b32_e32 v7, 16, v7
	v_add3_u32 v8, v18, v8, s26
	ds_read2_b32 v[40:41], v23 offset0:231 offset1:239
	v_and_or_b32 v7, v8, s27, v7
	s_waitcnt lgkmcnt(3)
	v_bfe_u32 v8, v20, 16, 1
	v_add3_u32 v8, v20, v8, s26
	s_waitcnt lgkmcnt(2)
	v_bfe_u32 v9, v36, 16, 1
	v_lshrrev_b32_e32 v8, 16, v8
	v_add3_u32 v9, v36, v9, s26
	v_and_or_b32 v8, v9, s27, v8
	s_waitcnt lgkmcnt(1)
	v_bfe_u32 v9, v38, 16, 1
	v_add3_u32 v9, v38, v9, s26
	s_waitcnt lgkmcnt(0)
	v_bfe_u32 v10, v40, 16, 1
	v_lshrrev_b32_e32 v9, 16, v9
	v_add3_u32 v10, v40, v10, s26
	v_and_or_b32 v9, v10, s27, v9
	v_or_b32_e32 v10, s23, v22
	v_lshlrev_b32_e32 v42, 12, v10
	v_mov_b32_e32 v43, v3
	v_lshl_add_u64 v[42:43], v[12:13], 0, v[42:43]
	global_store_dwordx4 v[42:43], v[6:9], off sc1
	v_bfe_u32 v10, v41, 16, 1
	v_add3_u32 v10, v41, v10, s26
	v_bfe_u32 v6, v11, 16, 1
	v_add3_u32 v6, v11, v6, s26
	v_bfe_u32 v7, v15, 16, 1
	v_lshrrev_b32_e32 v6, 16, v6
	v_add3_u32 v7, v15, v7, s26
	v_and_or_b32 v6, v7, s27, v6
	v_bfe_u32 v7, v17, 16, 1
	v_add3_u32 v7, v17, v7, s26
	v_bfe_u32 v8, v19, 16, 1
	v_lshrrev_b32_e32 v7, 16, v7
	v_add3_u32 v8, v19, v8, s26
	v_and_or_b32 v7, v8, s27, v7
	v_bfe_u32 v8, v21, 16, 1
	v_add3_u32 v8, v21, v8, s26
	v_bfe_u32 v9, v37, 16, 1
	v_lshrrev_b32_e32 v8, 16, v8
	v_add3_u32 v9, v37, v9, s26
	v_and_or_b32 v8, v9, s27, v8
	v_bfe_u32 v9, v39, 16, 1
	v_add3_u32 v9, v39, v9, s26
	v_lshrrev_b32_e32 v9, 16, v9
	v_and_or_b32 v9, v10, s27, v9
	v_or_b32_e32 v10, s23, v24
	v_lshlrev_b32_e32 v10, 12, v10
	v_mov_b32_e32 v11, v3
	ds_read2_b32 v[14:15], v23 offset0:16 offset1:24
	v_lshl_add_u64 v[10:11], v[12:13], 0, v[10:11]
	global_store_dwordx4 v[10:11], v[6:9], off sc1
	ds_read2_b32 v[10:11], v23 offset0:49 offset1:57
	ds_read2_b32 v[16:17], v23 offset0:82 offset1:90
	ds_read2_b32 v[18:19], v23 offset0:115 offset1:123
	s_waitcnt lgkmcnt(3)
	v_bfe_u32 v6, v14, 16, 1
	v_add3_u32 v6, v14, v6, s26
	s_waitcnt lgkmcnt(2)
	v_bfe_u32 v7, v10, 16, 1
	ds_read2_b32 v[20:21], v23 offset0:148 offset1:156
	v_lshrrev_b32_e32 v6, 16, v6
	v_add3_u32 v7, v10, v7, s26
	ds_read2_b32 v[36:37], v23 offset0:181 offset1:189
	v_and_or_b32 v6, v7, s27, v6
	s_waitcnt lgkmcnt(3)
	v_bfe_u32 v7, v16, 16, 1
	v_add3_u32 v7, v16, v7, s26
	s_waitcnt lgkmcnt(2)
	v_bfe_u32 v8, v18, 16, 1
	ds_read2_b32 v[38:39], v23 offset0:214 offset1:222
	v_lshrrev_b32_e32 v7, 16, v7
	v_add3_u32 v8, v18, v8, s26
	ds_read2_b32 v[40:41], v23 offset0:247 offset1:255
	v_and_or_b32 v7, v8, s27, v7
	s_waitcnt lgkmcnt(3)
	v_bfe_u32 v8, v20, 16, 1
	v_add3_u32 v8, v20, v8, s26
	s_waitcnt lgkmcnt(2)
	v_bfe_u32 v9, v36, 16, 1
	v_lshrrev_b32_e32 v8, 16, v8
	v_add3_u32 v9, v36, v9, s26
	v_and_or_b32 v8, v9, s27, v8
	s_waitcnt lgkmcnt(1)
	v_bfe_u32 v9, v38, 16, 1
	v_add3_u32 v9, v38, v9, s26
	s_waitcnt lgkmcnt(0)
	v_bfe_u32 v10, v40, 16, 1
	v_lshrrev_b32_e32 v9, 16, v9
	v_add3_u32 v10, v40, v10, s26
	v_and_or_b32 v9, v10, s27, v9
	v_or_b32_e32 v10, s23, v25
	v_lshlrev_b32_e32 v42, 12, v10
	v_mov_b32_e32 v43, v3
	v_lshl_add_u64 v[42:43], v[12:13], 0, v[42:43]
	global_store_dwordx4 v[42:43], v[6:9], off sc1
	v_bfe_u32 v10, v41, 16, 1
	v_add3_u32 v10, v41, v10, s26
	v_bfe_u32 v6, v15, 16, 1
	v_add3_u32 v6, v15, v6, s26
	v_bfe_u32 v7, v11, 16, 1
	v_lshrrev_b32_e32 v6, 16, v6
	v_add3_u32 v7, v11, v7, s26
	v_and_or_b32 v6, v7, s27, v6
	v_bfe_u32 v7, v17, 16, 1
	v_add3_u32 v7, v17, v7, s26
	v_bfe_u32 v8, v19, 16, 1
	v_lshrrev_b32_e32 v7, 16, v7
	v_add3_u32 v8, v19, v8, s26
	v_and_or_b32 v7, v8, s27, v7
	v_bfe_u32 v8, v21, 16, 1
	v_add3_u32 v8, v21, v8, s26
	v_bfe_u32 v9, v37, 16, 1
	v_lshrrev_b32_e32 v8, 16, v8
	v_add3_u32 v9, v37, v9, s26
	v_and_or_b32 v8, v9, s27, v8
	v_bfe_u32 v9, v39, 16, 1
	v_add3_u32 v9, v39, v9, s26
	v_lshrrev_b32_e32 v9, 16, v9
	v_and_or_b32 v9, v10, s27, v9
	v_or_b32_e32 v10, s23, v26
	v_lshlrev_b32_e32 v10, 12, v10
	v_mov_b32_e32 v11, v3
	v_lshl_add_u64 v[10:11], v[12:13], 0, v[10:11]
	global_store_dwordx4 v[10:11], v[6:9], off sc1
	s_waitcnt lgkmcnt(0)

.LBB0_49:
	v_lshl_add_u64 v[36:37], v[20:21], 0, s[20:21]
	v_lshl_add_u64 v[38:39], v[18:19], 0, s[20:21]
	v_lshl_add_u64 v[40:41], v[16:17], 0, s[20:21]
	v_lshl_add_u64 v[42:43], v[14:15], 0, s[20:21]
	v_lshl_add_u64 v[44:45], v[12:13], 0, s[20:21]
	v_lshl_add_u64 v[46:47], v[10:11], 0, s[20:21]
	v_lshl_add_u64 v[48:49], v[8:9], 0, s[20:21]
	v_lshl_add_u64 v[50:51], v[6:7], 0, s[20:21]
	global_load_dword v52, v[36:37], off nt
	global_load_dword v53, v[38:39], off nt
	global_load_dword v54, v[40:41], off nt
	global_load_dword v55, v[42:43], off nt
	global_load_dword v56, v[44:45], off nt
	global_load_dword v57, v[46:47], off nt
	global_load_dword v58, v[48:49], off nt
	global_load_dword v59, v[50:51], off nt
	s_add_u32 s20, s20, 0x20000
	s_addc_u32 s21, s21, 0
	v_lshl_add_u64 v[36:37], v[20:21], 0, s[20:21]
	v_lshl_add_u64 v[38:39], v[18:19], 0, s[20:21]
	v_lshl_add_u64 v[40:41], v[16:17], 0, s[20:21]
	v_lshl_add_u64 v[42:43], v[14:15], 0, s[20:21]
	v_lshl_add_u64 v[44:45], v[12:13], 0, s[20:21]
	v_lshl_add_u64 v[46:47], v[10:11], 0, s[20:21]
	v_lshl_add_u64 v[48:49], v[8:9], 0, s[20:21]
	v_lshl_add_u64 v[50:51], v[6:7], 0, s[20:21]
	global_load_dword v60, v[36:37], off nt
	global_load_dword v61, v[38:39], off nt
	global_load_dword v62, v[40:41], off nt
	global_load_dword v63, v[42:43], off nt
	global_load_dword v64, v[44:45], off nt
	global_load_dword v65, v[46:47], off nt
	global_load_dword v66, v[48:49], off nt
	global_load_dword v67, v[50:51], off nt
	s_add_u32 s20, s20, 0x20000
	s_addc_u32 s21, s21, 0
	v_lshl_add_u64 v[36:37], v[20:21], 0, s[20:21]
	v_lshl_add_u64 v[38:39], v[18:19], 0, s[20:21]
	v_lshl_add_u64 v[40:41], v[16:17], 0, s[20:21]
	v_lshl_add_u64 v[42:43], v[14:15], 0, s[20:21]
	v_lshl_add_u64 v[44:45], v[12:13], 0, s[20:21]
	v_lshl_add_u64 v[46:47], v[10:11], 0, s[20:21]
	v_lshl_add_u64 v[48:49], v[8:9], 0, s[20:21]
	v_lshl_add_u64 v[50:51], v[6:7], 0, s[20:21]
	global_load_dword v68, v[36:37], off nt
	global_load_dword v69, v[38:39], off nt
	global_load_dword v70, v[40:41], off nt
	global_load_dword v71, v[42:43], off nt
	global_load_dword v72, v[44:45], off nt
	global_load_dword v73, v[46:47], off nt
	global_load_dword v74, v[48:49], off nt
	global_load_dword v75, v[50:51], off nt
	s_add_u32 s20, s20, 0x20000
	s_addc_u32 s21, s21, 0
	v_lshl_add_u64 v[36:37], v[20:21], 0, s[20:21]
	v_lshl_add_u64 v[38:39], v[18:19], 0, s[20:21]
	v_lshl_add_u64 v[40:41], v[16:17], 0, s[20:21]
	v_lshl_add_u64 v[42:43], v[14:15], 0, s[20:21]
	v_lshl_add_u64 v[44:45], v[12:13], 0, s[20:21]
	v_lshl_add_u64 v[46:47], v[10:11], 0, s[20:21]
	v_lshl_add_u64 v[48:49], v[8:9], 0, s[20:21]
	v_lshl_add_u64 v[50:51], v[6:7], 0, s[20:21]
	global_load_dword v76, v[36:37], off nt
	global_load_dword v77, v[38:39], off nt
	global_load_dword v78, v[40:41], off nt
	global_load_dword v79, v[42:43], off nt
	global_load_dword v80, v[44:45], off nt
	global_load_dword v81, v[46:47], off nt
	global_load_dword v82, v[48:49], off nt
	global_load_dword v83, v[50:51], off nt
	s_add_u32 s20, s20, 0x20000
	s_addc_u32 s21, s21, 0
	v_add_u32_e32 v36, 0x400, v35
	s_waitcnt vmcnt(30)
	ds_write2_b32 v35, v52, v53 offset1:66
	s_waitcnt vmcnt(28)
	ds_write2_b32 v35, v54, v55 offset0:132 offset1:198
	s_waitcnt vmcnt(26)
	ds_write2_b32 v36, v56, v57 offset0:8 offset1:74
	s_waitcnt vmcnt(24)
	ds_write2_b32 v36, v58, v59 offset0:140 offset1:206
	v_add_u32_e32 v35, 0x840, v35
	v_add_u32_e32 v36, 0x400, v35
	s_waitcnt vmcnt(22)
	ds_write2_b32 v35, v60, v61 offset1:66
	s_waitcnt vmcnt(20)
	ds_write2_b32 v35, v62, v63 offset0:132 offset1:198
	s_waitcnt vmcnt(18)
	ds_write2_b32 v36, v64, v65 offset0:8 offset1:74
	s_waitcnt vmcnt(16)
	ds_write2_b32 v36, v66, v67 offset0:140 offset1:206
	v_add_u32_e32 v35, 0x840, v35
	v_add_u32_e32 v36, 0x400, v35
	s_waitcnt vmcnt(14)
	ds_write2_b32 v35, v68, v69 offset1:66
	s_waitcnt vmcnt(12)
	ds_write2_b32 v35, v70, v71 offset0:132 offset1:198
	s_waitcnt vmcnt(10)
	ds_write2_b32 v36, v72, v73 offset0:8 offset1:74
	s_waitcnt vmcnt(8)
	ds_write2_b32 v36, v74, v75 offset0:140 offset1:206
	v_add_u32_e32 v35, 0x840, v35
	v_add_u32_e32 v36, 0x400, v35
	s_waitcnt vmcnt(6)
	ds_write2_b32 v35, v76, v77 offset1:66
	s_waitcnt vmcnt(4)
	ds_write2_b32 v35, v78, v79 offset0:132 offset1:198
	s_waitcnt vmcnt(2)
	ds_write2_b32 v36, v80, v81 offset0:8 offset1:74
	s_waitcnt vmcnt(0)
	ds_write2_b32 v36, v82, v83 offset0:140 offset1:206
	v_add_u32_e32 v35, 0x840, v35
	s_waitcnt lgkmcnt(0)
	s_lshl_b32 s20, s22, 5
	ds_read2_b32 v[10:11], v23 offset1:8
	s_and_b32 s23, s20, 0x7e0
	s_lshl_b32 s19, s19, 1
	ds_read2_b32 v[14:15], v23 offset0:33 offset1:41
	s_add_u32 s20, s30, s19
	s_addc_u32 s21, s31, 0
	ds_read2_b32 v[16:17], v23 offset0:66 offset1:74
	v_lshl_add_u64 v[6:7], s[20:21], 0, v[2:3]
	ds_read2_b32 v[18:19], v23 offset0:99 offset1:107
	v_lshl_add_u64 v[12:13], v[6:7], 0, s[16:17]
	s_waitcnt lgkmcnt(3)
	v_bfe_u32 v6, v10, 16, 1
	v_add3_u32 v6, v10, v6, s26
	s_waitcnt lgkmcnt(2)
	v_bfe_u32 v7, v14, 16, 1
	ds_read2_b32 v[20:21], v23 offset0:132 offset1:140
	v_lshrrev_b32_e32 v6, 16, v6
	v_add3_u32 v7, v14, v7, s26
	ds_read2_b32 v[36:37], v23 offset0:165 offset1:173
	v_and_or_b32 v6, v7, s27, v6
	s_waitcnt lgkmcnt(3)
	v_bfe_u32 v7, v16, 16, 1
	v_add3_u32 v7, v16, v7, s26
	s_waitcnt lgkmcnt(2)
	v_bfe_u32 v8, v18, 16, 1
	ds_read2_b32 v[38:39], v23 offset0:198 offset1:206
	v_lshrrev_b32_e32 v7, 16, v7
	v_add3_u32 v8, v18, v8, s26
	ds_read2_b32 v[40:41], v23 offset0:231 offset1:239
	v_and_or_b32 v7, v8, s27, v7
	s_waitcnt lgkmcnt(3)
	v_bfe_u32 v8, v20, 16, 1
	v_add3_u32 v8, v20, v8, s26
	s_waitcnt lgkmcnt(2)
	v_bfe_u32 v9, v36, 16, 1
	v_lshrrev_b32_e32 v8, 16, v8
	v_add3_u32 v9, v36, v9, s26
	v_and_or_b32 v8, v9, s27, v8
	s_waitcnt lgkmcnt(1)
	v_bfe_u32 v9, v38, 16, 1
	v_add3_u32 v9, v38, v9, s26
	s_waitcnt lgkmcnt(0)
	v_bfe_u32 v10, v40, 16, 1
	v_lshrrev_b32_e32 v9, 16, v9
	v_add3_u32 v10, v40, v10, s26
	v_and_or_b32 v9, v10, s27, v9
	v_or_b32_e32 v10, s23, v22
	v_mul_u32_u24_e32 v10, 0x1600, v10
	v_lshlrev_b32_e32 v42, 1, v10
	v_mov_b32_e32 v43, v3
	v_lshl_add_u64 v[42:43], v[12:13], 0, v[42:43]
	global_store_dwordx4 v[42:43], v[6:9], off sc1
	v_bfe_u32 v10, v41, 16, 1
	v_add3_u32 v10, v41, v10, s26
	v_bfe_u32 v6, v11, 16, 1
	v_add3_u32 v6, v11, v6, s26
	v_bfe_u32 v7, v15, 16, 1
	v_lshrrev_b32_e32 v6, 16, v6
	v_add3_u32 v7, v15, v7, s26
	v_and_or_b32 v6, v7, s27, v6
	v_bfe_u32 v7, v17, 16, 1
	v_add3_u32 v7, v17, v7, s26
	v_bfe_u32 v8, v19, 16, 1
	v_lshrrev_b32_e32 v7, 16, v7
	v_add3_u32 v8, v19, v8, s26
	v_and_or_b32 v7, v8, s27, v7
	v_bfe_u32 v8, v21, 16, 1
	v_add3_u32 v8, v21, v8, s26
	v_bfe_u32 v9, v37, 16, 1
	v_lshrrev_b32_e32 v8, 16, v8
	v_add3_u32 v9, v37, v9, s26
	v_and_or_b32 v8, v9, s27, v8
	v_bfe_u32 v9, v39, 16, 1
	v_add3_u32 v9, v39, v9, s26
	v_lshrrev_b32_e32 v9, 16, v9
	v_and_or_b32 v9, v10, s27, v9
	v_or_b32_e32 v10, s23, v24
	v_mul_u32_u24_e32 v10, 0x1600, v10
	v_lshlrev_b32_e32 v10, 1, v10
	v_mov_b32_e32 v11, v3
	ds_read2_b32 v[14:15], v23 offset0:16 offset1:24
	v_lshl_add_u64 v[10:11], v[12:13], 0, v[10:11]
	global_store_dwordx4 v[10:11], v[6:9], off sc1
	ds_read2_b32 v[10:11], v23 offset0:49 offset1:57
	ds_read2_b32 v[16:17], v23 offset0:82 offset1:90
	ds_read2_b32 v[18:19], v23 offset0:115 offset1:123
	s_waitcnt lgkmcnt(3)
	v_bfe_u32 v6, v14, 16, 1
	v_add3_u32 v6, v14, v6, s26
	s_waitcnt lgkmcnt(2)
	v_bfe_u32 v7, v10, 16, 1
	ds_read2_b32 v[20:21], v23 offset0:148 offset1:156
	v_lshrrev_b32_e32 v6, 16, v6
	v_add3_u32 v7, v10, v7, s26
	ds_read2_b32 v[36:37], v23 offset0:181 offset1:189
	v_and_or_b32 v6, v7, s27, v6
	s_waitcnt lgkmcnt(3)
	v_bfe_u32 v7, v16, 16, 1
	v_add3_u32 v7, v16, v7, s26
	s_waitcnt lgkmcnt(2)
	v_bfe_u32 v8, v18, 16, 1
	ds_read2_b32 v[38:39], v23 offset0:214 offset1:222
	v_lshrrev_b32_e32 v7, 16, v7
	v_add3_u32 v8, v18, v8, s26
	ds_read2_b32 v[40:41], v23 offset0:247 offset1:255
	v_and_or_b32 v7, v8, s27, v7
	s_waitcnt lgkmcnt(3)
	v_bfe_u32 v8, v20, 16, 1
	v_add3_u32 v8, v20, v8, s26
	s_waitcnt lgkmcnt(2)
	v_bfe_u32 v9, v36, 16, 1
	v_lshrrev_b32_e32 v8, 16, v8
	v_add3_u32 v9, v36, v9, s26
	v_and_or_b32 v8, v9, s27, v8
	s_waitcnt lgkmcnt(1)
	v_bfe_u32 v9, v38, 16, 1
	v_add3_u32 v9, v38, v9, s26
	s_waitcnt lgkmcnt(0)
	v_bfe_u32 v10, v40, 16, 1
	v_lshrrev_b32_e32 v9, 16, v9
	v_add3_u32 v10, v40, v10, s26
	v_and_or_b32 v9, v10, s27, v9
	v_or_b32_e32 v10, s23, v25
	v_mul_u32_u24_e32 v10, 0x1600, v10
	v_lshlrev_b32_e32 v42, 1, v10
	v_mov_b32_e32 v43, v3
	v_lshl_add_u64 v[42:43], v[12:13], 0, v[42:43]
	global_store_dwordx4 v[42:43], v[6:9], off sc1
	v_bfe_u32 v10, v41, 16, 1
	v_add3_u32 v10, v41, v10, s26
	v_bfe_u32 v6, v15, 16, 1
	v_add3_u32 v6, v15, v6, s26
	v_bfe_u32 v7, v11, 16, 1
	v_lshrrev_b32_e32 v6, 16, v6
	v_add3_u32 v7, v11, v7, s26
	v_and_or_b32 v6, v7, s27, v6
	v_bfe_u32 v7, v17, 16, 1
	v_add3_u32 v7, v17, v7, s26
	v_bfe_u32 v8, v19, 16, 1
	v_lshrrev_b32_e32 v7, 16, v7
	v_add3_u32 v8, v19, v8, s26
	v_and_or_b32 v7, v8, s27, v7
	v_bfe_u32 v8, v21, 16, 1
	v_add3_u32 v8, v21, v8, s26
	v_bfe_u32 v9, v37, 16, 1
	v_lshrrev_b32_e32 v8, 16, v8
	v_add3_u32 v9, v37, v9, s26
	v_and_or_b32 v8, v9, s27, v8
	v_bfe_u32 v9, v39, 16, 1
	v_add3_u32 v9, v39, v9, s26
	v_lshrrev_b32_e32 v9, 16, v9
	v_and_or_b32 v9, v10, s27, v9
	v_or_b32_e32 v10, s23, v26
	v_mul_u32_u24_e32 v10, 0x1600, v10
	v_lshlrev_b32_e32 v10, 1, v10
	v_mov_b32_e32 v11, v3
	v_lshl_add_u64 v[10:11], v[12:13], 0, v[10:11]
	global_store_dwordx4 v[10:11], v[6:9], off sc1
	s_waitcnt lgkmcnt(0)

.LBB0_54:
	v_lshl_add_u64 v[36:37], v[20:21], 0, s[20:21]
	v_lshl_add_u64 v[38:39], v[18:19], 0, s[20:21]
	v_lshl_add_u64 v[40:41], v[16:17], 0, s[20:21]
	v_lshl_add_u64 v[42:43], v[14:15], 0, s[20:21]
	v_lshl_add_u64 v[44:45], v[12:13], 0, s[20:21]
	v_lshl_add_u64 v[46:47], v[10:11], 0, s[20:21]
	v_lshl_add_u64 v[48:49], v[8:9], 0, s[20:21]
	v_lshl_add_u64 v[50:51], v[6:7], 0, s[20:21]
	global_load_dword v52, v[36:37], off nt
	global_load_dword v53, v[38:39], off nt
	global_load_dword v54, v[40:41], off nt
	global_load_dword v55, v[42:43], off nt
	global_load_dword v56, v[44:45], off nt
	global_load_dword v57, v[46:47], off nt
	global_load_dword v58, v[48:49], off nt
	global_load_dword v59, v[50:51], off nt
	s_add_u32 s20, s20, 0x58000
	s_addc_u32 s21, s21, 0
	v_lshl_add_u64 v[36:37], v[20:21], 0, s[20:21]
	v_lshl_add_u64 v[38:39], v[18:19], 0, s[20:21]
	v_lshl_add_u64 v[40:41], v[16:17], 0, s[20:21]
	v_lshl_add_u64 v[42:43], v[14:15], 0, s[20:21]
	v_lshl_add_u64 v[44:45], v[12:13], 0, s[20:21]
	v_lshl_add_u64 v[46:47], v[10:11], 0, s[20:21]
	v_lshl_add_u64 v[48:49], v[8:9], 0, s[20:21]
	v_lshl_add_u64 v[50:51], v[6:7], 0, s[20:21]
	global_load_dword v60, v[36:37], off nt
	global_load_dword v61, v[38:39], off nt
	global_load_dword v62, v[40:41], off nt
	global_load_dword v63, v[42:43], off nt
	global_load_dword v64, v[44:45], off nt
	global_load_dword v65, v[46:47], off nt
	global_load_dword v66, v[48:49], off nt
	global_load_dword v67, v[50:51], off nt
	s_add_u32 s20, s20, 0x58000
	s_addc_u32 s21, s21, 0
	v_lshl_add_u64 v[36:37], v[20:21], 0, s[20:21]
	v_lshl_add_u64 v[38:39], v[18:19], 0, s[20:21]
	v_lshl_add_u64 v[40:41], v[16:17], 0, s[20:21]
	v_lshl_add_u64 v[42:43], v[14:15], 0, s[20:21]
	v_lshl_add_u64 v[44:45], v[12:13], 0, s[20:21]
	v_lshl_add_u64 v[46:47], v[10:11], 0, s[20:21]
	v_lshl_add_u64 v[48:49], v[8:9], 0, s[20:21]
	v_lshl_add_u64 v[50:51], v[6:7], 0, s[20:21]
	global_load_dword v68, v[36:37], off nt
	global_load_dword v69, v[38:39], off nt
	global_load_dword v70, v[40:41], off nt
	global_load_dword v71, v[42:43], off nt
	global_load_dword v72, v[44:45], off nt
	global_load_dword v73, v[46:47], off nt
	global_load_dword v74, v[48:49], off nt
	global_load_dword v75, v[50:51], off nt
	s_add_u32 s20, s20, 0x58000
	s_addc_u32 s21, s21, 0
	v_lshl_add_u64 v[36:37], v[20:21], 0, s[20:21]
	v_lshl_add_u64 v[38:39], v[18:19], 0, s[20:21]
	v_lshl_add_u64 v[40:41], v[16:17], 0, s[20:21]
	v_lshl_add_u64 v[42:43], v[14:15], 0, s[20:21]
	v_lshl_add_u64 v[44:45], v[12:13], 0, s[20:21]
	v_lshl_add_u64 v[46:47], v[10:11], 0, s[20:21]
	v_lshl_add_u64 v[48:49], v[8:9], 0, s[20:21]
	v_lshl_add_u64 v[50:51], v[6:7], 0, s[20:21]
	global_load_dword v76, v[36:37], off nt
	global_load_dword v77, v[38:39], off nt
	global_load_dword v78, v[40:41], off nt
	global_load_dword v79, v[42:43], off nt
	global_load_dword v80, v[44:45], off nt
	global_load_dword v81, v[46:47], off nt
	global_load_dword v82, v[48:49], off nt
	global_load_dword v83, v[50:51], off nt
	s_add_u32 s20, s20, 0x58000
	s_addc_u32 s21, s21, 0
	v_add_u32_e32 v36, 0x400, v35
	s_waitcnt vmcnt(30)
	ds_write2_b32 v35, v52, v53 offset1:66
	s_waitcnt vmcnt(28)
	ds_write2_b32 v35, v54, v55 offset0:132 offset1:198
	s_waitcnt vmcnt(26)
	ds_write2_b32 v36, v56, v57 offset0:8 offset1:74
	s_waitcnt vmcnt(24)
	ds_write2_b32 v36, v58, v59 offset0:140 offset1:206
	v_add_u32_e32 v35, 0x840, v35
	v_add_u32_e32 v36, 0x400, v35
	s_waitcnt vmcnt(22)
	ds_write2_b32 v35, v60, v61 offset1:66
	s_waitcnt vmcnt(20)
	ds_write2_b32 v35, v62, v63 offset0:132 offset1:198
	s_waitcnt vmcnt(18)
	ds_write2_b32 v36, v64, v65 offset0:8 offset1:74
	s_waitcnt vmcnt(16)
	ds_write2_b32 v36, v66, v67 offset0:140 offset1:206
	v_add_u32_e32 v35, 0x840, v35
	v_add_u32_e32 v36, 0x400, v35
	s_waitcnt vmcnt(14)
	ds_write2_b32 v35, v68, v69 offset1:66
	s_waitcnt vmcnt(12)
	ds_write2_b32 v35, v70, v71 offset0:132 offset1:198
	s_waitcnt vmcnt(10)
	ds_write2_b32 v36, v72, v73 offset0:8 offset1:74
	s_waitcnt vmcnt(8)
	ds_write2_b32 v36, v74, v75 offset0:140 offset1:206
	v_add_u32_e32 v35, 0x840, v35
	v_add_u32_e32 v36, 0x400, v35
	s_waitcnt vmcnt(6)
	ds_write2_b32 v35, v76, v77 offset1:66
	s_waitcnt vmcnt(4)
	ds_write2_b32 v35, v78, v79 offset0:132 offset1:198
	s_waitcnt vmcnt(2)
	ds_write2_b32 v36, v80, v81 offset0:8 offset1:74
	s_waitcnt vmcnt(0)
	ds_write2_b32 v36, v82, v83 offset0:140 offset1:206
	v_add_u32_e32 v35, 0x840, v35
	s_waitcnt lgkmcnt(0)
	ds_read2_b32 v[10:11], v23 offset1:8
	ds_read2_b32 v[14:15], v23 offset0:33 offset1:41
	ds_read2_b32 v[16:17], v23 offset0:66 offset1:74
	ds_read2_b32 v[18:19], v23 offset0:99 offset1:107
	ds_read2_b32 v[20:21], v23 offset0:132 offset1:140
	s_waitcnt lgkmcnt(4)
	v_bfe_u32 v6, v10, 16, 1
	v_add3_u32 v6, v10, v6, s26
	s_waitcnt lgkmcnt(3)
	v_bfe_u32 v7, v14, 16, 1
	v_lshrrev_b32_e32 v6, 16, v6
	v_add3_u32 v7, v14, v7, s26
	ds_read2_b32 v[36:37], v23 offset0:165 offset1:173
	v_and_or_b32 v6, v7, s27, v6
	s_waitcnt lgkmcnt(3)
	v_bfe_u32 v7, v16, 16, 1
	v_add3_u32 v7, v16, v7, s26
	s_waitcnt lgkmcnt(2)
	v_bfe_u32 v8, v18, 16, 1
	ds_read2_b32 v[38:39], v23 offset0:198 offset1:206
	v_lshrrev_b32_e32 v7, 16, v7
	v_add3_u32 v8, v18, v8, s26
	ds_read2_b32 v[40:41], v23 offset0:231 offset1:239
	v_and_or_b32 v7, v8, s27, v7
	s_waitcnt lgkmcnt(3)
	v_bfe_u32 v8, v20, 16, 1
	s_lshl_b32 s20, s23, 5
	s_lshl_b32 s21, s23, 6
	v_add3_u32 v8, v20, v8, s26
	s_waitcnt lgkmcnt(2)
	v_bfe_u32 v9, v36, 16, 1
	s_and_b32 s21, s21, 0x3f00
	s_and_b32 s20, s20, 0x60
	v_lshrrev_b32_e32 v8, 16, v8
	v_add3_u32 v9, v36, v9, s26
	s_or_b32 s20, s21, s20
	s_and_b32 s19, 0xffff, s19
	v_and_or_b32 v8, v9, s27, v8
	s_waitcnt lgkmcnt(1)
	v_bfe_u32 v9, v38, 16, 1
	s_or_b32 s23, s20, 0x80
	s_lshl_b32 s19, s19, 1
	v_add3_u32 v9, v38, v9, s26
	s_waitcnt lgkmcnt(0)
	v_bfe_u32 v10, v40, 16, 1
	s_add_u32 s20, s30, s19
	v_lshrrev_b32_e32 v9, 16, v9
	v_add3_u32 v10, v40, v10, s26
	s_addc_u32 s21, s31, 0
	v_and_or_b32 v9, v10, s27, v9
	v_or_b32_e32 v10, s23, v22
	v_lshl_add_u64 v[12:13], s[20:21], 0, v[2:3]
	v_lshlrev_b32_e32 v42, 12, v10
	v_mov_b32_e32 v43, v3
	v_lshl_add_u64 v[42:43], v[12:13], 0, v[42:43]
	global_store_dwordx4 v[42:43], v[6:9], off sc1
	v_bfe_u32 v10, v41, 16, 1
	v_add3_u32 v10, v41, v10, s26
	v_bfe_u32 v6, v11, 16, 1
	v_add3_u32 v6, v11, v6, s26
	v_bfe_u32 v7, v15, 16, 1
	v_lshrrev_b32_e32 v6, 16, v6
	v_add3_u32 v7, v15, v7, s26
	v_and_or_b32 v6, v7, s27, v6
	v_bfe_u32 v7, v17, 16, 1
	v_add3_u32 v7, v17, v7, s26
	v_bfe_u32 v8, v19, 16, 1
	v_lshrrev_b32_e32 v7, 16, v7
	v_add3_u32 v8, v19, v8, s26
	v_and_or_b32 v7, v8, s27, v7
	v_bfe_u32 v8, v21, 16, 1
	v_add3_u32 v8, v21, v8, s26
	v_bfe_u32 v9, v37, 16, 1
	v_lshrrev_b32_e32 v8, 16, v8
	v_add3_u32 v9, v37, v9, s26
	v_and_or_b32 v8, v9, s27, v8
	v_bfe_u32 v9, v39, 16, 1
	v_add3_u32 v9, v39, v9, s26
	v_lshrrev_b32_e32 v9, 16, v9
	v_and_or_b32 v9, v10, s27, v9
	v_or_b32_e32 v10, s23, v24
	v_lshlrev_b32_e32 v10, 12, v10
	v_mov_b32_e32 v11, v3
	ds_read2_b32 v[14:15], v23 offset0:16 offset1:24
	v_lshl_add_u64 v[10:11], v[12:13], 0, v[10:11]
	global_store_dwordx4 v[10:11], v[6:9], off sc1
	ds_read2_b32 v[10:11], v23 offset0:49 offset1:57
	ds_read2_b32 v[16:17], v23 offset0:82 offset1:90
	ds_read2_b32 v[18:19], v23 offset0:115 offset1:123
	s_waitcnt lgkmcnt(3)
	v_bfe_u32 v6, v14, 16, 1
	v_add3_u32 v6, v14, v6, s26
	s_waitcnt lgkmcnt(2)
	v_bfe_u32 v7, v10, 16, 1
	ds_read2_b32 v[20:21], v23 offset0:148 offset1:156
	v_lshrrev_b32_e32 v6, 16, v6
	v_add3_u32 v7, v10, v7, s26
	ds_read2_b32 v[36:37], v23 offset0:181 offset1:189
	v_and_or_b32 v6, v7, s27, v6
	s_waitcnt lgkmcnt(3)
	v_bfe_u32 v7, v16, 16, 1
	v_add3_u32 v7, v16, v7, s26
	s_waitcnt lgkmcnt(2)
	v_bfe_u32 v8, v18, 16, 1
	ds_read2_b32 v[38:39], v23 offset0:214 offset1:222
	v_lshrrev_b32_e32 v7, 16, v7
	v_add3_u32 v8, v18, v8, s26
	ds_read2_b32 v[40:41], v23 offset0:247 offset1:255
	v_and_or_b32 v7, v8, s27, v7
	s_waitcnt lgkmcnt(3)
	v_bfe_u32 v8, v20, 16, 1
	v_add3_u32 v8, v20, v8, s26
	s_waitcnt lgkmcnt(2)
	v_bfe_u32 v9, v36, 16, 1
	v_lshrrev_b32_e32 v8, 16, v8
	v_add3_u32 v9, v36, v9, s26
	v_and_or_b32 v8, v9, s27, v8
	s_waitcnt lgkmcnt(1)
	v_bfe_u32 v9, v38, 16, 1
	v_add3_u32 v9, v38, v9, s26
	s_waitcnt lgkmcnt(0)
	v_bfe_u32 v10, v40, 16, 1
	v_lshrrev_b32_e32 v9, 16, v9
	v_add3_u32 v10, v40, v10, s26
	v_and_or_b32 v9, v10, s27, v9
	v_or_b32_e32 v10, s23, v25
	v_lshlrev_b32_e32 v42, 12, v10
	v_mov_b32_e32 v43, v3
	v_lshl_add_u64 v[42:43], v[12:13], 0, v[42:43]
	global_store_dwordx4 v[42:43], v[6:9], off sc1
	v_bfe_u32 v10, v41, 16, 1
	v_add3_u32 v10, v41, v10, s26
	v_bfe_u32 v6, v15, 16, 1
	v_add3_u32 v6, v15, v6, s26
	v_bfe_u32 v7, v11, 16, 1
	v_lshrrev_b32_e32 v6, 16, v6
	v_add3_u32 v7, v11, v7, s26
	v_and_or_b32 v6, v7, s27, v6
	v_bfe_u32 v7, v17, 16, 1
	v_add3_u32 v7, v17, v7, s26
	v_bfe_u32 v8, v19, 16, 1
	v_lshrrev_b32_e32 v7, 16, v7
	v_add3_u32 v8, v19, v8, s26
	v_and_or_b32 v7, v8, s27, v7
	v_bfe_u32 v8, v21, 16, 1
	v_add3_u32 v8, v21, v8, s26
	v_bfe_u32 v9, v37, 16, 1
	v_lshrrev_b32_e32 v8, 16, v8
	v_add3_u32 v9, v37, v9, s26
	v_and_or_b32 v8, v9, s27, v8
	v_bfe_u32 v9, v39, 16, 1
	v_add3_u32 v9, v39, v9, s26
	v_lshrrev_b32_e32 v9, 16, v9
	v_and_or_b32 v9, v10, s27, v9
	v_or_b32_e32 v10, s23, v26
	v_lshlrev_b32_e32 v10, 12, v10
	v_mov_b32_e32 v11, v3
	v_lshl_add_u64 v[10:11], v[12:13], 0, v[10:11]
	global_store_dwordx4 v[10:11], v[6:9], off sc1
	s_waitcnt lgkmcnt(0)

.LBB0_59:
	v_lshl_add_u64 v[36:37], v[20:21], 0, s[22:23]
	v_lshl_add_u64 v[38:39], v[18:19], 0, s[22:23]
	v_lshl_add_u64 v[40:41], v[16:17], 0, s[22:23]
	v_lshl_add_u64 v[42:43], v[14:15], 0, s[22:23]
	v_lshl_add_u64 v[44:45], v[12:13], 0, s[22:23]
	v_lshl_add_u64 v[46:47], v[10:11], 0, s[22:23]
	v_lshl_add_u64 v[48:49], v[8:9], 0, s[22:23]
	v_lshl_add_u64 v[50:51], v[6:7], 0, s[22:23]
	global_load_dword v52, v[36:37], off nt
	global_load_dword v53, v[38:39], off nt
	global_load_dword v54, v[40:41], off nt
	global_load_dword v55, v[42:43], off nt
	global_load_dword v56, v[44:45], off nt
	global_load_dword v57, v[46:47], off nt
	global_load_dword v58, v[48:49], off nt
	global_load_dword v59, v[50:51], off nt
	s_add_u32 s22, s22, 0x58000
	s_addc_u32 s23, s23, 0
	v_lshl_add_u64 v[36:37], v[20:21], 0, s[22:23]
	v_lshl_add_u64 v[38:39], v[18:19], 0, s[22:23]
	v_lshl_add_u64 v[40:41], v[16:17], 0, s[22:23]
	v_lshl_add_u64 v[42:43], v[14:15], 0, s[22:23]
	v_lshl_add_u64 v[44:45], v[12:13], 0, s[22:23]
	v_lshl_add_u64 v[46:47], v[10:11], 0, s[22:23]
	v_lshl_add_u64 v[48:49], v[8:9], 0, s[22:23]
	v_lshl_add_u64 v[50:51], v[6:7], 0, s[22:23]
	global_load_dword v60, v[36:37], off nt
	global_load_dword v61, v[38:39], off nt
	global_load_dword v62, v[40:41], off nt
	global_load_dword v63, v[42:43], off nt
	global_load_dword v64, v[44:45], off nt
	global_load_dword v65, v[46:47], off nt
	global_load_dword v66, v[48:49], off nt
	global_load_dword v67, v[50:51], off nt
	s_add_u32 s22, s22, 0x58000
	s_addc_u32 s23, s23, 0
	v_lshl_add_u64 v[36:37], v[20:21], 0, s[22:23]
	v_lshl_add_u64 v[38:39], v[18:19], 0, s[22:23]
	v_lshl_add_u64 v[40:41], v[16:17], 0, s[22:23]
	v_lshl_add_u64 v[42:43], v[14:15], 0, s[22:23]
	v_lshl_add_u64 v[44:45], v[12:13], 0, s[22:23]
	v_lshl_add_u64 v[46:47], v[10:11], 0, s[22:23]
	v_lshl_add_u64 v[48:49], v[8:9], 0, s[22:23]
	v_lshl_add_u64 v[50:51], v[6:7], 0, s[22:23]
	global_load_dword v68, v[36:37], off nt
	global_load_dword v69, v[38:39], off nt
	global_load_dword v70, v[40:41], off nt
	global_load_dword v71, v[42:43], off nt
	global_load_dword v72, v[44:45], off nt
	global_load_dword v73, v[46:47], off nt
	global_load_dword v74, v[48:49], off nt
	global_load_dword v75, v[50:51], off nt
	s_add_u32 s22, s22, 0x58000
	s_addc_u32 s23, s23, 0
	v_lshl_add_u64 v[36:37], v[20:21], 0, s[22:23]
	v_lshl_add_u64 v[38:39], v[18:19], 0, s[22:23]
	v_lshl_add_u64 v[40:41], v[16:17], 0, s[22:23]
	v_lshl_add_u64 v[42:43], v[14:15], 0, s[22:23]
	v_lshl_add_u64 v[44:45], v[12:13], 0, s[22:23]
	v_lshl_add_u64 v[46:47], v[10:11], 0, s[22:23]
	v_lshl_add_u64 v[48:49], v[8:9], 0, s[22:23]
	v_lshl_add_u64 v[50:51], v[6:7], 0, s[22:23]
	global_load_dword v76, v[36:37], off nt
	global_load_dword v77, v[38:39], off nt
	global_load_dword v78, v[40:41], off nt
	global_load_dword v79, v[42:43], off nt
	global_load_dword v80, v[44:45], off nt
	global_load_dword v81, v[46:47], off nt
	global_load_dword v82, v[48:49], off nt
	global_load_dword v83, v[50:51], off nt
	s_add_u32 s22, s22, 0x58000
	s_addc_u32 s23, s23, 0
	v_add_u32_e32 v36, 0x400, v35
	s_waitcnt vmcnt(30)
	ds_write2_b32 v35, v52, v53 offset1:66
	s_waitcnt vmcnt(28)
	ds_write2_b32 v35, v54, v55 offset0:132 offset1:198
	s_waitcnt vmcnt(26)
	ds_write2_b32 v36, v56, v57 offset0:8 offset1:74
	s_waitcnt vmcnt(24)
	ds_write2_b32 v36, v58, v59 offset0:140 offset1:206
	v_add_u32_e32 v35, 0x840, v35
	v_add_u32_e32 v36, 0x400, v35
	s_waitcnt vmcnt(22)
	ds_write2_b32 v35, v60, v61 offset1:66
	s_waitcnt vmcnt(20)
	ds_write2_b32 v35, v62, v63 offset0:132 offset1:198
	s_waitcnt vmcnt(18)
	ds_write2_b32 v36, v64, v65 offset0:8 offset1:74
	s_waitcnt vmcnt(16)
	ds_write2_b32 v36, v66, v67 offset0:140 offset1:206
	v_add_u32_e32 v35, 0x840, v35
	v_add_u32_e32 v36, 0x400, v35
	s_waitcnt vmcnt(14)
	ds_write2_b32 v35, v68, v69 offset1:66
	s_waitcnt vmcnt(12)
	ds_write2_b32 v35, v70, v71 offset0:132 offset1:198
	s_waitcnt vmcnt(10)
	ds_write2_b32 v36, v72, v73 offset0:8 offset1:74
	s_waitcnt vmcnt(8)
	ds_write2_b32 v36, v74, v75 offset0:140 offset1:206
	v_add_u32_e32 v35, 0x840, v35
	v_add_u32_e32 v36, 0x400, v35
	s_waitcnt vmcnt(6)
	ds_write2_b32 v35, v76, v77 offset1:66
	s_waitcnt vmcnt(4)
	ds_write2_b32 v35, v78, v79 offset0:132 offset1:198
	s_waitcnt vmcnt(2)
	ds_write2_b32 v36, v80, v81 offset0:8 offset1:74
	s_waitcnt vmcnt(0)
	ds_write2_b32 v36, v82, v83 offset0:140 offset1:206
	v_add_u32_e32 v35, 0x840, v35
	s_waitcnt lgkmcnt(0)
	ds_read2_b32 v[10:11], v23 offset1:8
	ds_read2_b32 v[14:15], v23 offset0:33 offset1:41
	ds_read2_b32 v[16:17], v23 offset0:66 offset1:74
	ds_read2_b32 v[18:19], v23 offset0:99 offset1:107
	ds_read2_b32 v[20:21], v23 offset0:132 offset1:140
	s_waitcnt lgkmcnt(4)
	v_bfe_u32 v6, v10, 16, 1
	v_add3_u32 v6, v10, v6, s26
	s_waitcnt lgkmcnt(3)
	v_bfe_u32 v7, v14, 16, 1
	v_lshrrev_b32_e32 v6, 16, v6
	v_add3_u32 v7, v14, v7, s26
	ds_read2_b32 v[36:37], v23 offset0:165 offset1:173
	v_and_or_b32 v6, v7, s27, v6
	s_waitcnt lgkmcnt(3)
	v_bfe_u32 v7, v16, 16, 1
	v_add3_u32 v7, v16, v7, s26
	s_waitcnt lgkmcnt(2)
	v_bfe_u32 v8, v18, 16, 1
	ds_read2_b32 v[38:39], v23 offset0:198 offset1:206
	s_lshl_b32 s19, s19, 6
	v_lshrrev_b32_e32 v7, 16, v7
	v_add3_u32 v8, v18, v8, s26
	ds_read2_b32 v[40:41], v23 offset0:231 offset1:239
	s_and_b32 s19, s19, 0xffffff00
	s_and_b32 s20, s20, 0x60
	v_and_or_b32 v7, v8, s27, v7
	s_waitcnt lgkmcnt(3)
	v_bfe_u32 v8, v20, 16, 1
	s_or_b32 s20, s20, s19
	s_ashr_i32 s19, s18, 31
	v_add3_u32 v8, v20, v8, s26
	s_waitcnt lgkmcnt(2)
	v_bfe_u32 v9, v36, 16, 1
	s_lshl_b64 s[18:19], s[18:19], 1
	v_lshrrev_b32_e32 v8, 16, v8
	v_add3_u32 v9, v36, v9, s26
	s_add_u32 s18, s30, s18
	v_and_or_b32 v8, v9, s27, v8
	s_waitcnt lgkmcnt(1)
	v_bfe_u32 v9, v38, 16, 1
	v_or_b32_e32 v42, s20, v22
	s_addc_u32 s19, s31, s19
	v_add3_u32 v9, v38, v9, s26
	s_waitcnt lgkmcnt(0)
	v_bfe_u32 v10, v40, 16, 1
	v_ashrrev_i32_e32 v43, 31, v42
	v_lshl_add_u64 v[12:13], s[18:19], 0, v[2:3]
	v_lshrrev_b32_e32 v9, 16, v9
	v_add3_u32 v10, v40, v10, s26
	v_lshlrev_b64 v[42:43], 12, v[42:43]
	v_and_or_b32 v9, v10, s27, v9
	v_lshl_add_u64 v[42:43], v[12:13], 0, v[42:43]
	global_store_dwordx4 v[42:43], v[6:9], off sc1
	v_bfe_u32 v10, v41, 16, 1
	v_add3_u32 v10, v41, v10, s26
	v_bfe_u32 v6, v11, 16, 1
	v_add3_u32 v6, v11, v6, s26
	v_bfe_u32 v7, v15, 16, 1
	v_lshrrev_b32_e32 v6, 16, v6
	v_add3_u32 v7, v15, v7, s26
	v_and_or_b32 v6, v7, s27, v6
	v_bfe_u32 v7, v17, 16, 1
	v_add3_u32 v7, v17, v7, s26
	v_bfe_u32 v8, v19, 16, 1
	v_lshrrev_b32_e32 v7, 16, v7
	v_add3_u32 v8, v19, v8, s26
	v_and_or_b32 v7, v8, s27, v7
	v_bfe_u32 v8, v21, 16, 1
	v_add3_u32 v8, v21, v8, s26
	v_bfe_u32 v9, v37, 16, 1
	v_lshrrev_b32_e32 v8, 16, v8
	v_add3_u32 v9, v37, v9, s26
	v_and_or_b32 v8, v9, s27, v8
	v_bfe_u32 v9, v39, 16, 1
	v_add3_u32 v9, v39, v9, s26
	v_lshrrev_b32_e32 v9, 16, v9
	v_and_or_b32 v9, v10, s27, v9
	v_or_b32_e32 v10, s20, v24
	v_ashrrev_i32_e32 v11, 31, v10
	v_lshlrev_b64 v[10:11], 12, v[10:11]
	ds_read2_b32 v[14:15], v23 offset0:16 offset1:24
	v_lshl_add_u64 v[10:11], v[12:13], 0, v[10:11]
	global_store_dwordx4 v[10:11], v[6:9], off sc1
	ds_read2_b32 v[10:11], v23 offset0:49 offset1:57
	ds_read2_b32 v[16:17], v23 offset0:82 offset1:90
	ds_read2_b32 v[18:19], v23 offset0:115 offset1:123
	s_waitcnt lgkmcnt(3)
	v_bfe_u32 v6, v14, 16, 1
	v_add3_u32 v6, v14, v6, s26
	s_waitcnt lgkmcnt(2)
	v_bfe_u32 v7, v10, 16, 1
	ds_read2_b32 v[20:21], v23 offset0:148 offset1:156
	v_lshrrev_b32_e32 v6, 16, v6
	v_add3_u32 v7, v10, v7, s26
	ds_read2_b32 v[36:37], v23 offset0:181 offset1:189
	v_and_or_b32 v6, v7, s27, v6
	s_waitcnt lgkmcnt(3)
	v_bfe_u32 v7, v16, 16, 1
	v_add3_u32 v7, v16, v7, s26
	s_waitcnt lgkmcnt(2)
	v_bfe_u32 v8, v18, 16, 1
	ds_read2_b32 v[38:39], v23 offset0:214 offset1:222
	v_lshrrev_b32_e32 v7, 16, v7
	v_add3_u32 v8, v18, v8, s26
	ds_read2_b32 v[40:41], v23 offset0:247 offset1:255
	v_and_or_b32 v7, v8, s27, v7
	s_waitcnt lgkmcnt(3)
	v_bfe_u32 v8, v20, 16, 1
	v_add3_u32 v8, v20, v8, s26
	s_waitcnt lgkmcnt(2)
	v_bfe_u32 v9, v36, 16, 1
	v_lshrrev_b32_e32 v8, 16, v8
	v_add3_u32 v9, v36, v9, s26
	v_and_or_b32 v8, v9, s27, v8
	s_waitcnt lgkmcnt(1)
	v_bfe_u32 v9, v38, 16, 1
	v_or_b32_e32 v42, s20, v25
	v_add3_u32 v9, v38, v9, s26
	s_waitcnt lgkmcnt(0)
	v_bfe_u32 v10, v40, 16, 1
	v_ashrrev_i32_e32 v43, 31, v42
	v_lshrrev_b32_e32 v9, 16, v9
	v_add3_u32 v10, v40, v10, s26
	v_lshlrev_b64 v[42:43], 12, v[42:43]
	v_and_or_b32 v9, v10, s27, v9
	v_lshl_add_u64 v[42:43], v[12:13], 0, v[42:43]
	global_store_dwordx4 v[42:43], v[6:9], off sc1
	v_bfe_u32 v10, v41, 16, 1
	v_add3_u32 v10, v41, v10, s26
	v_bfe_u32 v6, v15, 16, 1
	v_add3_u32 v6, v15, v6, s26
	v_bfe_u32 v7, v11, 16, 1
	v_lshrrev_b32_e32 v6, 16, v6
	v_add3_u32 v7, v11, v7, s26
	v_and_or_b32 v6, v7, s27, v6
	v_bfe_u32 v7, v17, 16, 1
	v_add3_u32 v7, v17, v7, s26
	v_bfe_u32 v8, v19, 16, 1
	v_lshrrev_b32_e32 v7, 16, v7
	v_add3_u32 v8, v19, v8, s26
	v_and_or_b32 v7, v8, s27, v7
	v_bfe_u32 v8, v21, 16, 1
	v_add3_u32 v8, v21, v8, s26
	v_bfe_u32 v9, v37, 16, 1
	v_lshrrev_b32_e32 v8, 16, v8
	v_add3_u32 v9, v37, v9, s26
	v_and_or_b32 v8, v9, s27, v8
	v_bfe_u32 v9, v39, 16, 1
	v_add3_u32 v9, v39, v9, s26
	v_lshrrev_b32_e32 v9, 16, v9
	v_and_or_b32 v9, v10, s27, v9
	v_or_b32_e32 v10, s20, v26
	v_ashrrev_i32_e32 v11, 31, v10
	v_lshlrev_b64 v[10:11], 12, v[10:11]
	v_lshl_add_u64 v[10:11], v[12:13], 0, v[10:11]
	global_store_dwordx4 v[10:11], v[6:9], off sc1
	s_waitcnt lgkmcnt(0)
	s_branch .LBB0_10
